# diff attention: P fragments keep the accumulator key order (no cross-half lane swaps); V^T LDS reads fetch V in the same order
# speedup vs baseline: 1.0384x; 1.0038x over previous
; #define LAS __attribute__((address_space(3)))
; DI int v_st(int k, int c) { const int kk = (k & ~0xC) | ((k & 4) << 1) | ((k & 8) >> 1); return ((kk >> 3) * 4 + (c >> 5)) * 512 + ((kk & 7) * 32 + (c & 31)) * 2; }
; DI int v_rd_base(int lane) { return ((lane & 3) << 3) | (((lane >> 2) & 3) << 6) | (((lane >> 4) & 1) << 5) | (((lane >> 5) & 1) << 8); }
; #define SLOAD(i, k0) do { sr_[i].vs0 = *reinterpret_cast<const bf16x8*>(&Vh[(long)((k0) + sr) * DV + sc]); sr_[i].vs1 = *reinterpret_cast<const bf16x8*>(&Vh[(long)((k0) + 32 + sr) * DV + sc]); \
;     _Pragma("unroll") for (int _c = 0; _c < NKC; ++_c) sr_[i].ks[_c] = *reinterpret_cast<const bf16x8*>(&Kh[(long)((k0) + krow[_c]) * DQK + kcol[_c]]); } while (0)
; template <int DQK, int SDEPTH, bool OUT_BF16, int QREG = DQK / 16, bool OUT_F16 = false> ...
;   constexpr int SHM_V = KVBLK * DV * 2, SHM_K = KVBLK * DQK * 2, NKC = DQK / 64, CPR = DQK / 8;
;   const float SCALE = (DQK == 64) ? 0.125f : ((DQK == 128) ? 0.088388347648318440f : 0.072168783648703220f);
;   const int wid = tid >> 6, lane = tid & 63, r32 = lane & 31, hi = lane >> 5;
;   LAS char* V_lds = lds; LAS char* K_lds = lds + 2 * SHM_V;
;   LAS float* ws = (LAS float*)(lds + 2 * SHM_V + 2 * SHM_K) + wid * 64; LAS float* li_l = ws; LAS float* al_l = ws + 32;
;   constexpr int QLDS = DQK / 16 - QREG;
;   LAS char* Qp = lds + 2 * SHM_V + 2 * SHM_K + NW * 64 * 4 + wid * (QLDS * 1024) + lane * 16;
;   float m_reg = -1e30f, l_reg = 0; f32x16 o[4] = {}; bf16x8 qr[QREG];
;   const bf16_t* Qw = Qb + (long)(wid * QBLK + r32) * DQK + hi * 8;
; #pragma unroll
;   for (int d0 = 0; d0 < QREG; ++d0) qr[d0] = *reinterpret_cast<const bf16x8*>(Qw + d0 * 16);
;     ...
;   const int sr = tid >> 4, sc = (tid & 15) * 8, vst0 = v_st(sr, sc), vst1 = v_st(32 + sr, sc);
;   int krow[NKC], kcol[NKC];
; #pragma unroll
;   for (int i = 0; i < NKC; ++i) { const int ci = tid + i * 512; krow[i] = ci / CPR; kcol[i] = (ci % CPR) * 8; }
;   const int vb0 = (int)(uintptr_t)V_lds + v_rd_base(lane);
;   struct { bf16x8 vs0, vs1, ks[NKC]; } sr_[SDEPTH];
;     ...
;   f32x16 pA0, pA1, pB0, pB1; float mnA, mnB, alA, alB; bf16x8 pa0, pa1, pa2, pa3; const int NT = seq / KVBLK;
;   constexpr int SE = 0, SO = SDEPTH - 1;
;   SLOAD(SE, 0); asm volatile("s_waitcnt vmcnt(0)" ::: "memory"); SWRITE(0, SE); __syncthreads();
.LBB0_781:
	s_add_i32 s2, s0, 0x100
	s_ashr_i32 s3, s2, 31
	s_and_b64 s[0:1], s[42:43], exec
	s_cselect_b32 s3, 0, s3
	s_cselect_b32 s2, 0, s2
	s_cmp_eq_u32 s8, 1
	s_cselect_b64 s[40:41], -1, 0
	s_and_b64 s[0:1], s[40:41], exec
	s_mul_i32 s10, s24, 0x2100
	s_cselect_b32 s28, 0x1080, 0
	s_mul_hi_i32 s8, s24, 0x2100
	s_add_u32 s0, s2, s10
	s_addc_u32 s1, s3, s8
	s_lshl_b64 s[0:1], s[0:1], 7
	s_add_u32 s0, s4, s0
	s_addc_u32 s1, s5, s1
	s_add_u32 s2, s10, s28
	s_addc_u32 s3, s8, 0
	s_lshl_b64 s[2:3], s[2:3], 7
	s_add_u32 s2, s4, s2
	s_addc_u32 s3, s5, s3
	s_mul_i32 s10, s25, 0x2100
	s_mul_hi_i32 s8, s25, 0x2100
	s_add_u32 s10, s10, s28
	s_addc_u32 s11, s8, 0
	s_lshl_b64 s[10:11], s[10:11], 8
	v_ashrrev_i32_e32 v4, 31, v2
	s_add_u32 s8, s4, s10
	v_lshrrev_b32_e32 v4, 29, v4
	s_addc_u32 s11, s5, s11
	v_ashrrev_i32_e32 v16, 4, v2
	v_add_u32_e32 v4, v2, v4
	s_add_u32 s10, s8, 0x37404000
	v_lshlrev_b32_e32 v3, 3, v58
	v_ashrrev_i32_e32 v20, 3, v4
	v_and_b32_e32 v4, -8, v4
	v_ashrrev_i32_e32 v17, 31, v16
	s_addc_u32 s11, s11, 0
	v_and_b32_e32 v0, 0x78, v3
	v_add_u32_e32 v18, 32, v16
	v_sub_u32_e32 v26, v2, v4
	v_lshlrev_b64 v[50:51], 8, v[16:17]
	v_lshlrev_b32_e32 v12, 3, v26
	v_lshl_add_u64 v[4:5], s[10:11], 0, v[50:51]
	v_lshlrev_b32_e32 v6, 1, v0
	v_mov_b32_e32 v7, v1
	v_ashrrev_i32_e32 v19, 31, v18
	v_ashrrev_i32_e32 v21, 31, v20
	v_lshl_add_u64 v[56:57], v[4:5], 0, v[6:7]
	v_lshlrev_b64 v[4:5], 8, v[18:19]
	v_ashrrev_i32_e32 v13, 31, v12
	v_lshlrev_b64 v[52:53], 7, v[20:21]
	v_lshl_add_u64 v[4:5], s[10:11], 0, v[4:5]
	v_lshl_add_u64 v[14:15], s[2:3], 0, v[52:53]
	v_lshlrev_b64 v[54:55], 1, v[12:13]
	v_lshl_add_u64 v[8:9], v[4:5], 0, v[6:7]
	v_lshl_add_u64 v[76:77], v[14:15], 0, v[54:55]
	s_mov_b32 s2, 0x36384000
	global_load_dwordx4 v[4:7], v[56:57], off
	s_nop 0
	global_load_dwordx4 v[8:11], v[8:9], off
	v_add_co_u32_e32 v12, vcc, s2, v76
	v_ashrrev_i32_e32 v17, 1, v2
	s_movk_i32 s2, 0xffe0
	v_addc_co_u32_e32 v13, vcc, 0, v77, vcc
	v_bfi_b32 v154, s2, v17, v58
	global_load_dwordx4 v[12:15], v[12:13], off
	v_ashrrev_i32_e32 v155, 31, v154
	v_bfe_u32 v166, v58, 5, 1
	v_lshlrev_b64 v[22:23], 7, v[154:155]
	v_lshl_add_u64 v[22:23], s[0:1], 0, v[22:23]
	v_lshlrev_b32_e32 v0, 4, v166
	v_lshl_add_u64 v[22:23], v[22:23], 0, v[0:1]
	s_mov_b32 s0, 0x35304000
	v_add_co_u32_e32 v24, vcc, s0, v22
	s_mov_b64 s[0:1], 0x35304000
	s_nop 0
	v_addc_co_u32_e32 v25, vcc, 0, v23, vcc
	global_load_dwordx4 v[110:113], v[24:25], off
	v_lshl_add_u64 v[22:23], v[22:23], 0, s[0:1]
	global_load_dwordx4 v[106:109], v[22:23], off offset:32
	global_load_dwordx4 v[102:105], v[22:23], off offset:64
	global_load_dwordx4 v[98:101], v[22:23], off offset:96
	v_and_b32_e32 v19, 0xfffff0, v16
	v_lshlrev_b32_e32 v21, 1, v16
	v_and_or_b32 v19, v21, 8, v19
	v_lshrrev_b32_e32 v24, 1, v16
	v_bfe_u32 v3, v3, 5, 2
	v_and_b32_e32 v16, 3, v16
	v_and_b32_e32 v21, 0xfffff0, v18
	v_lshlrev_b32_e32 v18, 1, v18
	v_lshrrev_b32_e32 v19, 1, v19
	v_lshlrev_b32_e32 v59, 4, v58
	v_and_or_b32 v16, v24, 4, v16
	v_and_or_b32 v18, v18, 8, v21
	v_or_b32_e32 v19, v19, v3
	v_and_b32_e32 v25, 48, v59
	v_lshlrev_b32_e32 v16, 6, v16
	v_lshrrev_b32_e32 v18, 1, v18
	v_lshlrev_b32_e32 v19, 9, v19
	v_or_b32_e32 v3, v18, v3
	v_or3_b32 v18, v19, v16, v25
	v_lshlrev_b32_e32 v3, 9, v3
	v_add_u32_e32 v172, 0, v18
	v_or3_b32 v3, v3, v16, v25
	s_waitcnt vmcnt(0)
	v_add_u32_e32 v173, 0, v3
	v_lshlrev_b32_e32 v3, 7, v20
	v_and_b32_e32 v167, 31, v58
	s_movk_i32 s0, 0x70
	v_and_b32_e32 v2, 0x3fffffc0, v2
	v_lshl_add_u32 v157, v2, 2, 0
	v_and_b32_e32 v78, 63, v58
	s_mul_hi_i32 s3, s25, 0x210000
	s_mul_i32 s25, s25, 0x210000
	s_mov_b32 s8, s9
	v_and_b32_e32 v156, 0xffffffe0, v17
	s_mov_b32 s10, s9
	s_mov_b32 s11, s9
	s_mov_b32 s12, s9
	s_mov_b32 s13, s9
	s_mov_b32 s14, s9
	s_mov_b32 s15, s9
	s_mov_b32 s16, s9
	s_mov_b32 s17, s9
	s_mov_b32 s18, s9
	s_mov_b32 s19, s9
	s_mov_b32 s20, s9
	s_mov_b32 s21, s9
	s_mov_b32 s22, s9
	s_mov_b32 s23, s9
	s_mov_b32 s46, 1
	v_lshl_add_u32 v168, v167, 2, v157
	v_mov_b32_e32 v170, 0
	s_waitcnt vmcnt(6)
	ds_write_b128 v172, v[4:7]
	v_bitop3_b32 v4, v20, v26, 7 bitop3:0x6c
	v_lshl_add_u32 v4, v4, 4, 0
	v_add_u32_e32 v174, v4, v3
	s_waitcnt vmcnt(5)
	ds_write_b128 v173, v[8:11]
	v_bitop3_b32 v3, v0, v59, s0 bitop3:0x78
	s_movk_i32 s0, 0x4000
	v_add_co_u32_e32 v2, vcc, s0, v56
	s_waitcnt vmcnt(4)
	ds_write_b128 v174, v[12:15] offset:32768
	v_lshl_add_u32 v12, v167, 7, 0
	v_add_u32_e32 v175, v12, v3
	s_waitcnt lgkmcnt(0)
	s_barrier
; DI void partialSM(f32x16& p0, f32x16& p1, float& m_reg, float& mn, float& alpha, const float SCALE) {
;   const float C = SCALE * 1.4426950408889634f;
;   float pmax = p0[0];
; #pragma unroll
;   for (int r = 1; r < 16; ++r) pmax = fmaxf(pmax, p0[r]);
; #pragma unroll
;   for (int r = 0; r < 16; ++r) pmax = fmaxf(pmax, p1[r]);
;   { auto rr = __builtin_amdgcn_permlane32_swap(__float_as_uint(pmax), __float_as_uint(pmax), false, false);
;     pmax = fmaxf(__uint_as_float(rr[0]), __uint_as_float(rr[1])); }
;   if (__builtin_expect(__all(pmax - m_reg <= THR / SCALE), 1)) { mn = m_reg; alpha = 1.f; }
;   else { mn = fmaxf(m_reg, pmax); alpha = __builtin_amdgcn_exp2f((m_reg - mn) * C); m_reg = mn; }
;   const float mnC = -mn * C;
; #pragma unroll
;   for (int r = 0; r < 16; ++r) p0[r] = fmaf(p0[r], C, mnC);
; #pragma unroll
;   for (int r = 0; r < 16; ++r) p1[r] = fmaf(p1[r], C, mnC);
; #pragma unroll
;   for (int r = 0; r < 16; ++r) p0[r] = __builtin_amdgcn_exp2f(p0[r]);
; }
	ds_read_b128 v[4:7], v175 offset:32768
	ds_read_b128 v[8:11], v175 offset:36864
	v_and_b32_e32 v13, 0x70, v59
	v_bitop3_b32 v3, v0, v13, 32 bitop3:0x36
	v_add_u32_e32 v176, v12, v3
	s_waitcnt vmcnt(3) lgkmcnt(1)
	v_mfma_f32_32x32x16_bf16 v[18:33], v[4:7], v[110:113], 0
	ds_read_b128 v[4:7], v176 offset:32768
	v_addc_co_u32_e32 v3, vcc, 0, v57, vcc
	s_movk_i32 s0, 0x6000
	v_lshlrev_b32_e32 v14, 3, v78
	s_waitcnt lgkmcnt(1)
	v_mfma_f32_32x32x16_bf16 v[34:49], v[8:11], v[110:113], 0
	ds_read_b128 v[8:11], v176 offset:36864
	s_waitcnt vmcnt(2) lgkmcnt(1)
	v_mfma_f32_32x32x16_bf16 v[18:33], v[4:7], v[106:109], v[18:33]
	v_add_co_u32_e32 v4, vcc, s0, v56
	s_mov_b32 s0, 0x36386000
	s_nop 0
	v_addc_co_u32_e32 v5, vcc, 0, v57, vcc
	v_bitop3_b32 v6, v0, v13, 64 bitop3:0x36
	global_load_dwordx4 v[60:63], v[2:3], off
	global_load_dwordx4 v[64:67], v[4:5], off
	v_add_co_u32_e32 v2, vcc, s0, v76
	v_add_u32_e32 v178, v12, v6
	s_nop 0
	v_addc_co_u32_e32 v3, vcc, 0, v77, vcc
	global_load_dwordx4 v[68:71], v[2:3], off
	ds_read_b128 v[2:5], v178 offset:32768
	v_and_b32_e32 v6, 0xc0, v59
	v_lshlrev_b32_e32 v7, 1, v58
	s_waitcnt lgkmcnt(1)
	v_mfma_f32_32x32x16_bf16 v[34:49], v[8:11], v[106:109], v[34:49]
	v_and_or_b32 v6, v14, 24, v6
	v_and_b32_e32 v7, 32, v7
	v_and_b32_e32 v8, 0x100, v14
	s_movk_i32 s0, 0x60
	v_or3_b32 v59, v6, v7, v8
	ds_read_b128 v[6:9], v178 offset:36864
	v_add_u32_e32 v171, 0, v59
	s_waitcnt vmcnt(4) lgkmcnt(1)
	v_mfma_f32_32x32x16_bf16 v[18:33], v[2:5], v[102:105], v[18:33]
	v_bitop3_b32 v2, v0, v13, s0 bitop3:0x36
	v_add_u32_e32 v177, v12, v2
	ds_read_b128 v[2:5], v177 offset:32768
	ds_read_b128 v[72:75], v177 offset:36864
	s_mov_b32 s0, 0x8000
	s_waitcnt lgkmcnt(2)
	v_mfma_f32_32x32x16_bf16 v[34:49], v[6:9], v[102:105], v[34:49]
	s_waitcnt vmcnt(3) lgkmcnt(1)
	v_mfma_f32_32x32x16_bf16 v[18:33], v[2:5], v[98:101], v[18:33]
	v_mov_b64_e32 v[2:3], s[8:9]
	v_mov_b64_e32 v[4:5], s[10:11]
	v_mov_b64_e32 v[6:7], s[12:13]
	v_mov_b64_e32 v[8:9], s[14:15]
	v_mov_b64_e32 v[10:11], s[16:17]
	v_mov_b64_e32 v[12:13], s[18:19]
	v_mov_b64_e32 v[14:15], s[20:21]
	s_waitcnt lgkmcnt(0)
	v_mfma_f32_32x32x16_bf16 v[34:49], v[72:75], v[98:101], v[34:49]
	s_nop 2
	v_max_f32_e32 v72, v19, v19
	v_max_f32_e32 v73, v18, v18
	v_max_f32_e32 v72, v73, v72
	v_max3_f32 v72, v72, v20, v21
	v_max3_f32 v72, v72, v22, v23
	v_max3_f32 v72, v72, v24, v25
	v_max3_f32 v72, v72, v26, v27
	v_max3_f32 v72, v72, v28, v29
	v_max3_f32 v72, v72, v30, v31
	v_max3_f32 v72, v72, v32, v33
	v_max3_f32 v72, v72, v34, v35
	v_max3_f32 v72, v72, v36, v37
	v_max3_f32 v72, v72, v38, v39
	v_max3_f32 v72, v72, v40, v41
	v_max3_f32 v72, v72, v42, v43
	v_max3_f32 v72, v72, v44, v45
	v_max3_f32 v72, v72, v46, v47
	v_max3_f32 v72, v72, v48, v49
	v_mov_b32_e32 v73, v72
	s_nop 1
	v_permlane32_swap_b32_e32 v72, v73
	v_max_f32_e32 v73, v73, v73
	v_max_f32_e32 v72, v72, v72
	v_max_f32_e32 v74, v72, v73
	v_add_f32_e32 v72, 0x7149f2ca, v74
	v_cmp_ge_f32_e32 vcc, 0x4138aa3b, v72
	v_add_co_u32_e64 v72, s[0:1], s0, v56
	s_cmp_eq_u64 vcc, exec
	s_nop 0
	v_addc_co_u32_e64 v73, s[0:1], 0, v57, s[0:1]
	s_mov_b32 s0, 0xa000
	s_nop 0
	v_add_co_u32_e64 v56, s[0:1], s0, v56
	global_load_dwordx4 v[114:117], v[72:73], off
	s_nop 0
	v_addc_co_u32_e64 v57, s[0:1], 0, v57, s[0:1]
	s_mov_b32 s0, 0x36388000
	s_nop 0
	v_add_co_u32_e64 v72, s[0:1], s0, v76
	s_cselect_b64 vcc, -1, 0
	s_nop 0
	v_addc_co_u32_e64 v73, s[0:1], 0, v77, s[0:1]
	global_load_dwordx4 v[118:121], v[56:57], off
	global_load_dwordx4 v[122:125], v[72:73], off
	v_max_f32_e32 v56, 0xf149f2ca, v74
	v_cndmask_b32_e32 v142, v56, v239, vcc
	v_sub_f32_e32 v57, 0xf149f2ca, v56
	v_mul_f32_e32 v56, 0xbf800000, v142
	v_fmamk_f32 v18, v18, 0x3f800000, v56
	v_exp_f32_e32 v146, v18
	v_fmamk_f32 v18, v19, 0x3f800000, v56
	v_exp_f32_e32 v148, v18
	v_fmamk_f32 v18, v20, 0x3f800000, v56
	v_exp_f32_e32 v150, v18
	v_fmamk_f32 v18, v21, 0x3f800000, v56
	v_exp_f32_e32 v152, v18
	v_fmamk_f32 v18, v22, 0x3f800000, v56
	v_exp_f32_e32 v162, v18
	v_fmamk_f32 v18, v23, 0x3f800000, v56
	v_exp_f32_e32 v164, v18
	v_fmamk_f32 v18, v24, 0x3f800000, v56
	v_exp_f32_e32 v165, v18
	v_fmamk_f32 v18, v25, 0x3f800000, v56
	v_exp_f32_e32 v186, v18
	v_fmamk_f32 v18, v26, 0x3f800000, v56
	v_mul_f32_e32 v57, 0x3f800000, v57
	v_exp_f32_e32 v144, v18
	v_fmamk_f32 v18, v27, 0x3f800000, v56
	s_add_i32 s2, 0, 0x4000
	v_exp_f32_e32 v57, v57
	v_exp_f32_e32 v145, v18
	v_fmamk_f32 v18, v28, 0x3f800000, v56
	v_add_u32_e32 v169, s2, v59
	s_lshl_b32 s2, s28, 8
	v_exp_f32_e32 v147, v18
	v_fmamk_f32 v18, v29, 0x3f800000, v56
	s_add_u32 s2, s25, s2
	v_exp_f32_e32 v149, v18
	v_fmamk_f32 v18, v30, 0x3f800000, v56
	s_addc_u32 s3, s3, 0
	v_mov_b64_e32 v[16:17], s[22:23]
	v_exp_f32_e32 v151, v18
	v_fmamk_f32 v18, v31, 0x3f800000, v56
	v_lshl_add_u64 v[158:159], s[2:3], 0, v[50:51]
	s_mul_i32 s2, s24, 0x108000
	s_lshl_b32 s8, s28, 7
	v_pk_fma_f32 v[126:127], v[48:49], s[34:35], v[56:57] op_sel_hi:[1,0,0]
	v_pk_fma_f32 v[132:133], v[46:47], s[34:35], v[56:57] op_sel_hi:[1,0,0]
	v_pk_fma_f32 v[136:137], v[44:45], s[34:35], v[56:57] op_sel_hi:[1,0,0]
	v_pk_fma_f32 v[128:129], v[42:43], s[34:35], v[56:57] op_sel_hi:[1,0,0]
	v_pk_fma_f32 v[130:131], v[40:41], s[34:35], v[56:57] op_sel_hi:[1,0,0]
	v_pk_fma_f32 v[134:135], v[38:39], s[34:35], v[56:57] op_sel_hi:[1,0,0]
	v_pk_fma_f32 v[138:139], v[36:37], s[34:35], v[56:57] op_sel_hi:[1,0,0]
	v_pk_fma_f32 v[140:141], v[34:35], s[34:35], v[56:57] op_sel_hi:[1,0,0]
	v_exp_f32_e32 v153, v18
	v_fmamk_f32 v18, v32, 0x3f800000, v56
	v_fmac_f32_e32 v56, 0x3f800000, v33
	s_mul_hi_i32 s3, s24, 0x108000
	s_add_u32 s2, s2, s8
	v_exp_f32_e32 v163, v18
	v_exp_f32_e32 v183, v56
	v_and_b32_e32 v18, 15, v58
	s_addc_u32 s3, s3, 0
	s_waitcnt vmcnt(3)
	v_lshl_or_b32 v158, v18, 4, v158
	v_lshl_add_u64 v[18:19], s[2:3], 0, v[52:53]
	s_waitcnt vmcnt(5)
	ds_write_b128 v172, v[60:63] offset:16384
	s_waitcnt vmcnt(4)
	ds_write_b128 v173, v[64:67] offset:16384
	s_waitcnt vmcnt(3)
	ds_write_b128 v174, v[68:71] offset:40960
	v_cndmask_b32_e64 v179, v57, 1.0, vcc
	v_lshl_add_u64 v[160:161], v[18:19], 0, v[54:55]
	v_mov_b64_e32 v[64:65], v[16:17]
	v_mov_b64_e32 v[48:49], v[16:17]
	v_mov_b64_e32 v[32:33], v[16:17]
	v_cmp_gt_u32_e64 s[0:1], 32, v78
	v_mov_b64_e32 v[62:63], v[14:15]
	v_mov_b64_e32 v[60:61], v[12:13]
	v_mov_b64_e32 v[58:59], v[10:11]
	v_mov_b64_e32 v[56:57], v[8:9]
	v_mov_b64_e32 v[54:55], v[6:7]
	v_mov_b64_e32 v[52:53], v[4:5]
	v_mov_b64_e32 v[50:51], v[2:3]
	v_mov_b64_e32 v[46:47], v[14:15]
	v_mov_b64_e32 v[44:45], v[12:13]
	v_mov_b64_e32 v[42:43], v[10:11]
	v_mov_b64_e32 v[40:41], v[8:9]
	v_mov_b64_e32 v[38:39], v[6:7]
	v_mov_b64_e32 v[36:37], v[4:5]
	v_mov_b64_e32 v[34:35], v[2:3]
	v_mov_b64_e32 v[30:31], v[14:15]
	v_mov_b64_e32 v[28:29], v[12:13]
	v_mov_b64_e32 v[26:27], v[10:11]
	v_mov_b64_e32 v[24:25], v[8:9]
	v_mov_b64_e32 v[22:23], v[6:7]
	v_mov_b64_e32 v[20:21], v[4:5]
	v_mov_b64_e32 v[18:19], v[2:3]
	s_waitcnt lgkmcnt(0)
	s_barrier
; #define SBAR() __builtin_amdgcn_sched_barrier(0)
; DI void finishSM(f32x16& p0, f32x16& p1, float alpha, float& l_reg, bf16x8& pa0, bf16x8& pa1, bf16x8& pa2, bf16x8& pa3) {
; #pragma unroll
;   for (int r = 0; r < 16; ++r) p1[r] = __builtin_amdgcn_exp2f(p1[r]);
;   float ps = 0;
; #pragma unroll
;   for (int r = 0; r < 16; ++r) ps += p0[r];
; #pragma unroll
;   for (int r = 0; r < 16; ++r) ps += p1[r];
;   { auto rr = __builtin_amdgcn_permlane32_swap(__float_as_uint(ps), __float_as_uint(ps), false, false);
;     ps = __uint_as_float(rr[0]) + __uint_as_float(rr[1]); }
;   l_reg = l_reg * alpha + ps;
;     ...
;   PK4(p0, 0, pa0); PK4(p0, 8, pa1); PK4(p1, 0, pa2); PK4(p1, 8, pa3);
;     ...
; }
; template <int D0> DI void pv_one(f32x16& od, int vb, bf16x8 pa0, bf16x8 pa1, bf16x8 pa2, bf16x8 pa3) {
;   const s16x4 l0 = tr_read<v_rd_off(D0, 0, 0)>(vb), h0 = tr_read<v_rd_off(D0, 0, 1)>(vb), l1 = tr_read<v_rd_off(D0, 1, 0)>(vb), h1 = tr_read<v_rd_off(D0, 1, 1)>(vb);
;   const s16x4 l2 = tr_read<v_rd_off(D0, 2, 0)>(vb), h2 = tr_read<v_rd_off(D0, 2, 1)>(vb), l3 = tr_read<v_rd_off(D0, 3, 0)>(vb), h3 = tr_read<v_rd_off(D0, 3, 1)>(vb);
;   asm volatile("s_waitcnt lgkmcnt(0)" ::: "memory"); SBAR();
;     ...
;   od = __builtin_amdgcn_mfma_f32_32x32x16_bf16(pa0, PK(l0, h0), od, 0, 0, 0);
;   od = __builtin_amdgcn_mfma_f32_32x32x16_bf16(pa1, PK(l1, h1), od, 0, 0, 0);
;   od = __builtin_amdgcn_mfma_f32_32x32x16_bf16(pa2, PK(l2, h2), od, 0, 0, 0);
;   od = __builtin_amdgcn_mfma_f32_32x32x16_bf16(pa3, PK(l3, h3), od, 0, 0, 0);
;     ...
; }
; DI void pv_d0(f32x16* o, int vb, bf16x8 pa0, bf16x8 pa1, bf16x8 pa2, bf16x8 pa3) {
;   pv_one<0>(o[0], vb, pa0, pa1, pa2, pa3); pv_one<1>(o[1], vb, pa0, pa1, pa2, pa3); pv_one<2>(o[2], vb, pa0, pa1, pa2, pa3); pv_one<3>(o[3], vb, pa0, pa1, pa2, pa3);
; }
; template <int DQK, int SDEPTH, bool OUT_BF16, int QREG = DQK / 16, bool OUT_F16 = false> ...
;     ...
;   SLOAD(SO, KVBLK); if constexpr (SDEPTH == 2) { if (2 < NT) SLOAD(SE, 2 * KVBLK); }
;   SWAIT(); SWRITE(1, SO); __syncthreads();
;   for (int j = 1; j + 1 < NT; j += 2) {
;     SBAR(); QKT(pB0, pB1, K_lds + SHM_K);
;     finishSM(pA0, pA1, alA, l_reg, pa0, pa1, pa2, pa3); SBAR();
;     SLOAD(SO, (j + SDEPTH) * KVBLK); SBAR();
;     pv_d0(o, vb0, pa0, pa1, pa2, pa3); partialSM(pB0, pB1, m_reg, mnB, alB, SCALE);
	v_exp_f32_e32 v140, v140
	v_exp_f32_e32 v141, v141
	v_exp_f32_e32 v138, v138
	v_exp_f32_e32 v139, v139
	v_exp_f32_e32 v134, v134
	v_exp_f32_e32 v135, v135
	v_exp_f32_e32 v130, v130
	v_exp_f32_e32 v131, v131
	v_exp_f32_e32 v128, v128
	v_exp_f32_e32 v129, v129
	v_exp_f32_e32 v136, v136
	v_exp_f32_e32 v137, v137
	v_exp_f32_e32 v132, v132
	v_exp_f32_e32 v133, v133
	v_exp_f32_e32 v126, v126
	v_exp_f32_e32 v127, v127
	v_mov_b32_e32 v206, v142
	v_mul_f32_e32 v205, 0xbf800000, v142
	v_add_f32_e32 v203, v146, v148
	v_add_f32_e32 v203, v150, v203
	v_add_f32_e32 v203, v152, v203
	v_add_f32_e32 v203, v162, v203
	v_add_f32_e32 v203, v164, v203
	v_add_f32_e32 v203, v165, v203
	v_add_f32_e32 v203, v186, v203
	v_add_f32_e32 v203, v144, v203
	v_add_f32_e32 v203, v145, v203
	v_add_f32_e32 v203, v147, v203
	v_add_f32_e32 v203, v149, v203
	v_add_f32_e32 v203, v151, v203
	v_add_f32_e32 v203, v153, v203
	v_add_f32_e32 v203, v163, v203
	v_add_f32_e32 v203, v183, v203
	v_add_f32_e32 v203, v140, v203
	v_add_f32_e32 v203, v141, v203
	v_add_f32_e32 v203, v138, v203
	v_add_f32_e32 v203, v139, v203
	v_add_f32_e32 v203, v134, v203
	v_add_f32_e32 v203, v135, v203
	v_add_f32_e32 v203, v130, v203
	v_add_f32_e32 v203, v131, v203
	v_add_f32_e32 v203, v128, v203
	v_add_f32_e32 v203, v129, v203
	v_add_f32_e32 v203, v136, v203
	v_add_f32_e32 v203, v137, v203
	v_add_f32_e32 v203, v132, v203
	v_add_f32_e32 v203, v133, v203
	v_add_f32_e32 v203, v126, v203
	v_add_f32_e32 v203, v127, v203
	v_cvt_pk_bf16_f32 v66, v146, v148
	v_cvt_pk_bf16_f32 v67, v150, v152
	v_cvt_pk_bf16_f32 v68, v162, v164
	v_cvt_pk_bf16_f32 v69, v165, v186
	v_cvt_pk_bf16_f32 v70, v144, v145
	v_cvt_pk_bf16_f32 v71, v147, v149
	v_cvt_pk_bf16_f32 v72, v151, v153
	v_cvt_pk_bf16_f32 v73, v163, v183
	v_cvt_pk_bf16_f32 v74, v140, v141
	v_cvt_pk_bf16_f32 v75, v138, v139
	v_cvt_pk_bf16_f32 v76, v134, v135
	v_cvt_pk_bf16_f32 v77, v130, v131
	v_cvt_pk_bf16_f32 v78, v128, v129
	v_cvt_pk_bf16_f32 v79, v136, v137
	v_cvt_pk_bf16_f32 v80, v132, v133
	v_cvt_pk_bf16_f32 v81, v126, v127
	v_bfe_u32 v231, v171, 8, 1
	v_mul_u32_u24_e32 v231, 0x700, v231
	v_add_u32_e32 v230, v171, v231
	v_add_u32_e32 v231, v169, v231
	v_mov_b32_e32 v138, v66
	v_mov_b32_e32 v139, v67
	v_mov_b32_e32 v140, v68
	v_mov_b32_e32 v141, v69
	v_mov_b32_e32 v144, v70
	v_mov_b32_e32 v145, v71
	v_mov_b32_e32 v146, v72
	v_mov_b32_e32 v147, v73
	v_mov_b32_e32 v148, v74
	v_mov_b32_e32 v149, v75
	v_mov_b32_e32 v150, v76
	v_mov_b32_e32 v151, v77
	v_mov_b32_e32 v162, v78
	v_mov_b32_e32 v163, v79
	v_mov_b32_e32 v164, v80
	v_mov_b32_e32 v165, v81
	v_mov_b32_e32 v170, v203
	v_mov_b32_e32 v214, v205
	v_mov_b32_e32 v215, v205
	v_mov_b32_e32 v216, v205
	v_mov_b32_e32 v217, v205
	v_mov_b32_e32 v218, v205
	v_mov_b32_e32 v219, v205
	v_mov_b32_e32 v220, v205
	v_mov_b32_e32 v221, v205
	v_mov_b32_e32 v222, v205
	v_mov_b32_e32 v223, v205
	v_mov_b32_e32 v224, v205
	v_mov_b32_e32 v225, v205
	v_mov_b32_e32 v226, v205
	v_mov_b32_e32 v227, v205
	v_mov_b32_e32 v228, v205
	v_mov_b32_e32 v229, v205
	s_add_u32 s80, s4, 0x37410000
	s_addc_u32 s81, s5, 0
	s_add_u32 s82, s4, 0x37412000
	s_addc_u32 s83, s5, 0
	s_add_u32 s84, s4, 0x3638a000
	s_addc_u32 s85, s5, 0
	s_add_u32 s86, s4, 0x37414000
	s_addc_u32 s87, s5, 0
	s_add_u32 s88, s4, 0x37416000
	s_addc_u32 s89, s5, 0
	s_add_u32 s90, s4, 0x3638c000
	s_addc_u32 s91, s5, 0
.LBB0_782:
	ds_read_b128 v[66:69], v175 offset:40960
	ds_read_b128 v[70:73], v175 offset:45056
	ds_read_b128 v[188:191], v176 offset:40960
	ds_read_b128 v[192:195], v176 offset:45056
	s_waitcnt lgkmcnt(3)
	v_mfma_f32_32x32x16_bf16 v[82:97], v[66:69], v[110:113], v[214:229]
	s_waitcnt lgkmcnt(2)
	v_mfma_f32_32x32x16_bf16 v[66:81], v[70:73], v[110:113], v[214:229]
	s_waitcnt lgkmcnt(1)
	v_mfma_f32_32x32x16_bf16 v[82:97], v[188:191], v[106:109], v[82:97]
	s_waitcnt lgkmcnt(0)
	v_mfma_f32_32x32x16_bf16 v[66:81], v[192:195], v[106:109], v[66:81]
	ds_read_b128 v[188:191], v178 offset:40960
	ds_read_b128 v[192:195], v178 offset:45056
	s_waitcnt lgkmcnt(1)
	v_mfma_f32_32x32x16_bf16 v[82:97], v[188:191], v[102:105], v[82:97]
	s_waitcnt lgkmcnt(0)
	v_mfma_f32_32x32x16_bf16 v[66:81], v[192:195], v[102:105], v[66:81]
	ds_read_b128 v[188:191], v177 offset:40960
	ds_read_b128 v[192:195], v177 offset:45056
	s_waitcnt lgkmcnt(1)
	v_mfma_f32_32x32x16_bf16 v[82:97], v[188:191], v[98:101], v[82:97]
	s_waitcnt lgkmcnt(0)
	v_mfma_f32_32x32x16_bf16 v[66:81], v[192:195], v[98:101], v[66:81]
	global_load_dwordx4 v[126:129], v158, s[80:81]
	global_load_dwordx4 v[130:133], v158, s[82:83]
	global_load_dwordx4 v[134:137], v160, s[84:85]
	ds_read_b64_tr_b16 v[186:187], v230 offset:0x0
	ds_read_b64_tr_b16 v[188:189], v230 offset:0x100
	ds_read_b64_tr_b16 v[190:191], v230 offset:0x1000
	ds_read_b64_tr_b16 v[192:193], v230 offset:0x1100
	ds_read_b64_tr_b16 v[194:195], v230 offset:0x2000
	ds_read_b64_tr_b16 v[196:197], v230 offset:0x2100
	ds_read_b64_tr_b16 v[198:199], v230 offset:0x3000
	ds_read_b64_tr_b16 v[200:201], v230 offset:0x3100
	s_waitcnt lgkmcnt(0)
	v_mfma_f32_32x32x16_bf16 v[2:17], v[138:141], v[186:189], v[2:17]
	ds_read_b64_tr_b16 v[186:187], v230 offset:0x200
	ds_read_b64_tr_b16 v[188:189], v230 offset:0x300
	v_exp_f32_e32 v82, v82
	v_exp_f32_e32 v83, v83
	v_exp_f32_e32 v84, v84
	v_exp_f32_e32 v85, v85
	v_exp_f32_e32 v86, v86
	v_mfma_f32_32x32x16_bf16 v[2:17], v[144:147], v[190:193], v[2:17]
	ds_read_b64_tr_b16 v[190:191], v230 offset:0x1200
	ds_read_b64_tr_b16 v[192:193], v230 offset:0x1300
	v_add_f32_e32 v180, v82, v83
	v_exp_f32_e32 v87, v87
	v_add_f32_e32 v180, v84, v180
	v_exp_f32_e32 v88, v88
	v_add_f32_e32 v180, v85, v180
	v_mfma_f32_32x32x16_bf16 v[2:17], v[148:151], v[194:197], v[2:17]
	ds_read_b64_tr_b16 v[194:195], v230 offset:0x2200
	ds_read_b64_tr_b16 v[196:197], v230 offset:0x2300
	v_cvt_pk_bf16_f32 v208, v82, v83
	v_exp_f32_e32 v89, v89
	v_add_f32_e32 v180, v86, v180
	v_exp_f32_e32 v90, v90
	v_add_f32_e32 v180, v87, v180
	v_mfma_f32_32x32x16_bf16 v[2:17], v[162:165], v[198:201], v[2:17]
	ds_read_b64_tr_b16 v[198:199], v230 offset:0x3200
	ds_read_b64_tr_b16 v[200:201], v230 offset:0x3300
	v_cvt_pk_bf16_f32 v209, v84, v85
	v_exp_f32_e32 v91, v91
	v_add_f32_e32 v180, v88, v180
	v_exp_f32_e32 v92, v92
	v_add_f32_e32 v180, v89, v180
	s_waitcnt lgkmcnt(0)
; #define SBAR() __builtin_amdgcn_sched_barrier(0)
; template <int OFF> DI s16x4 tr_read(int vb) { s16x4 r; asm volatile("ds_read_b64_tr_b16 %0, %1 offset:%2" : "=&v"(r) : "v"(vb), "i"(OFF) : "memory"); return r; }
; #define SWRITE(b, i) do { *(LAS bf16x8*)(V_lds + (b) * SHM_V + vst0) = sr_[i].vs0; *(LAS bf16x8*)(V_lds + (b) * SHM_V + vst1) = sr_[i].vs1; \
;     _Pragma("unroll") for (int _c = 0; _c < NKC; ++_c) *(LAS bf16x8*)(K_lds + (b) * SHM_K + kswz<DQK>(krow[_c], kcol[_c] * 2)) = sr_[i].ks[_c]; } while (0)
; #define SWAIT() do { if constexpr (SDEPTH == 2) { if constexpr (NKC == 1) asm volatile("s_waitcnt vmcnt(3)" ::: "memory"); else if constexpr (NKC == 2) asm volatile("s_waitcnt vmcnt(4)" ::: "memory"); else asm volatile("s_waitcnt vmcnt(5)" ::: "memory"); } \
;     else asm volatile("s_waitcnt vmcnt(0)" ::: "memory"); } while (0)
; template <int D0> DI void pv_one(f32x16& od, int vb, bf16x8 pa0, bf16x8 pa1, bf16x8 pa2, bf16x8 pa3) {
;   const s16x4 l0 = tr_read<v_rd_off(D0, 0, 0)>(vb), h0 = tr_read<v_rd_off(D0, 0, 1)>(vb), l1 = tr_read<v_rd_off(D0, 1, 0)>(vb), h1 = tr_read<v_rd_off(D0, 1, 1)>(vb);
;   const s16x4 l2 = tr_read<v_rd_off(D0, 2, 0)>(vb), h2 = tr_read<v_rd_off(D0, 2, 1)>(vb), l3 = tr_read<v_rd_off(D0, 3, 0)>(vb), h3 = tr_read<v_rd_off(D0, 3, 1)>(vb);
;   asm volatile("s_waitcnt lgkmcnt(0)" ::: "memory"); SBAR();
;     ...
;   od = __builtin_amdgcn_mfma_f32_32x32x16_bf16(pa0, PK(l0, h0), od, 0, 0, 0);
;   od = __builtin_amdgcn_mfma_f32_32x32x16_bf16(pa1, PK(l1, h1), od, 0, 0, 0);
;   od = __builtin_amdgcn_mfma_f32_32x32x16_bf16(pa2, PK(l2, h2), od, 0, 0, 0);
;   od = __builtin_amdgcn_mfma_f32_32x32x16_bf16(pa3, PK(l3, h3), od, 0, 0, 0);
;     ...
; }
; DI void pv_d0(f32x16* o, int vb, bf16x8 pa0, bf16x8 pa1, bf16x8 pa2, bf16x8 pa3) {
;   pv_one<0>(o[0], vb, pa0, pa1, pa2, pa3); pv_one<1>(o[1], vb, pa0, pa1, pa2, pa3); pv_one<2>(o[2], vb, pa0, pa1, pa2, pa3); pv_one<3>(o[3], vb, pa0, pa1, pa2, pa3);
; }
; template <int DQK, int SDEPTH, bool OUT_BF16, int QREG = DQK / 16, bool OUT_F16 = false> ...
;     ...
;     __syncthreads(); SWAIT(); SWRITE(0, SE);
;     RESC(alB); __syncthreads();
;     SBAR(); QKT(pA0, pA1, K_lds);
	v_mfma_f32_32x32x16_bf16 v[50:65], v[138:141], v[186:189], v[50:65]
	ds_read_b64_tr_b16 v[186:187], v230 offset:0x400
	ds_read_b64_tr_b16 v[188:189], v230 offset:0x500
	v_cvt_pk_bf16_f32 v210, v86, v87
	v_exp_f32_e32 v93, v93
	v_add_f32_e32 v180, v90, v180
	v_exp_f32_e32 v94, v94
	v_add_f32_e32 v180, v91, v180
	v_mfma_f32_32x32x16_bf16 v[50:65], v[144:147], v[190:193], v[50:65]
	ds_read_b64_tr_b16 v[190:191], v230 offset:0x1400
	ds_read_b64_tr_b16 v[192:193], v230 offset:0x1500
	v_cvt_pk_bf16_f32 v211, v88, v89
	v_exp_f32_e32 v95, v95
	v_add_f32_e32 v180, v92, v180
	v_exp_f32_e32 v96, v96
	v_add_f32_e32 v180, v93, v180
	v_mfma_f32_32x32x16_bf16 v[50:65], v[148:151], v[194:197], v[50:65]
	ds_read_b64_tr_b16 v[194:195], v230 offset:0x2400
	ds_read_b64_tr_b16 v[196:197], v230 offset:0x2500
	v_cvt_pk_bf16_f32 v244, v90, v91
	v_exp_f32_e32 v97, v97
	v_add_f32_e32 v180, v94, v180
	v_exp_f32_e32 v66, v66
	v_add_f32_e32 v180, v95, v180
	v_mfma_f32_32x32x16_bf16 v[50:65], v[162:165], v[198:201], v[50:65]
	ds_read_b64_tr_b16 v[198:199], v230 offset:0x3400
	ds_read_b64_tr_b16 v[200:201], v230 offset:0x3500
	v_cvt_pk_bf16_f32 v245, v92, v93
	v_exp_f32_e32 v67, v67
	v_add_f32_e32 v180, v96, v180
	v_exp_f32_e32 v68, v68
	v_add_f32_e32 v180, v97, v180
	s_waitcnt lgkmcnt(0)
	v_mfma_f32_32x32x16_bf16 v[34:49], v[138:141], v[186:189], v[34:49]
	ds_read_b64_tr_b16 v[186:187], v230 offset:0x600
	ds_read_b64_tr_b16 v[188:189], v230 offset:0x700
	v_cvt_pk_bf16_f32 v246, v94, v95
	v_exp_f32_e32 v69, v69
	v_add_f32_e32 v180, v66, v180
	v_exp_f32_e32 v70, v70
	v_add_f32_e32 v180, v67, v180
	v_cvt_pk_bf16_f32 v247, v96, v97
	v_mfma_f32_32x32x16_bf16 v[34:49], v[144:147], v[190:193], v[34:49]
	ds_read_b64_tr_b16 v[190:191], v230 offset:0x1600
	ds_read_b64_tr_b16 v[192:193], v230 offset:0x1700
	v_exp_f32_e32 v71, v71
	v_add_f32_e32 v180, v68, v180
	v_exp_f32_e32 v72, v72
	v_add_f32_e32 v180, v69, v180
	v_cvt_pk_bf16_f32 v248, v66, v67
	v_mfma_f32_32x32x16_bf16 v[34:49], v[148:151], v[194:197], v[34:49]
	ds_read_b64_tr_b16 v[194:195], v230 offset:0x2600
	ds_read_b64_tr_b16 v[196:197], v230 offset:0x2700
	v_exp_f32_e32 v73, v73
	v_add_f32_e32 v180, v70, v180
	v_exp_f32_e32 v74, v74
	v_add_f32_e32 v180, v71, v180
	v_cvt_pk_bf16_f32 v249, v68, v69
	v_mfma_f32_32x32x16_bf16 v[34:49], v[162:165], v[198:201], v[34:49]
	ds_read_b64_tr_b16 v[198:199], v230 offset:0x3600
	ds_read_b64_tr_b16 v[200:201], v230 offset:0x3700
	v_exp_f32_e32 v75, v75
	v_add_f32_e32 v180, v72, v180
	v_exp_f32_e32 v76, v76
	v_add_f32_e32 v180, v73, v180
	v_cvt_pk_bf16_f32 v250, v70, v71
	s_waitcnt lgkmcnt(0)
	v_mfma_f32_32x32x16_bf16 v[18:33], v[138:141], v[186:189], v[18:33]
	v_exp_f32_e32 v77, v77
	v_add_f32_e32 v180, v74, v180
	v_exp_f32_e32 v78, v78
	v_add_f32_e32 v180, v75, v180
	v_cvt_pk_bf16_f32 v251, v72, v73
	v_mfma_f32_32x32x16_bf16 v[18:33], v[144:147], v[190:193], v[18:33]
	v_exp_f32_e32 v79, v79
	v_add_f32_e32 v180, v76, v180
	v_exp_f32_e32 v80, v80
	v_add_f32_e32 v180, v77, v180
	v_cvt_pk_bf16_f32 v182, v74, v75
	v_mfma_f32_32x32x16_bf16 v[18:33], v[148:151], v[194:197], v[18:33]
	v_exp_f32_e32 v81, v81
	v_add_f32_e32 v180, v78, v180
	v_add_f32_e32 v180, v79, v180
	v_cvt_pk_bf16_f32 v183, v76, v77
	v_add_f32_e32 v180, v80, v180
	v_mfma_f32_32x32x16_bf16 v[18:33], v[162:165], v[198:201], v[18:33]
	v_add_f32_e32 v180, v81, v180
	v_cvt_pk_bf16_f32 v184, v78, v79
	v_cvt_pk_bf16_f32 v185, v80, v81
	v_cmp_nge_f32_e32 vcc, 0x453a4f54, v180
	v_add_f32_e32 v207, v170, v180
	s_barrier
	s_waitcnt vmcnt(3)
	ds_write_b128 v172, v[114:117]
	ds_write_b128 v173, v[118:121]
	ds_write_b128 v174, v[122:125] offset:32768
	s_cbranch_vccz .LBB0_786
	ds_read_b128 v[66:69], v175 offset:40960
	ds_read_b128 v[70:73], v175 offset:45056
	ds_read_b128 v[188:191], v176 offset:40960
	ds_read_b128 v[192:195], v176 offset:45056
	s_waitcnt lgkmcnt(3)
	v_mfma_f32_32x32x16_bf16 v[82:97], v[66:69], v[110:113], 0
	s_waitcnt lgkmcnt(2)
	v_mfma_f32_32x32x16_bf16 v[66:81], v[70:73], v[110:113], 0
	s_waitcnt lgkmcnt(1)
	v_mfma_f32_32x32x16_bf16 v[82:97], v[188:191], v[106:109], v[82:97]
	s_waitcnt lgkmcnt(0)
	v_mfma_f32_32x32x16_bf16 v[66:81], v[192:195], v[106:109], v[66:81]
	ds_read_b128 v[188:191], v178 offset:40960
	ds_read_b128 v[192:195], v178 offset:45056
	s_waitcnt lgkmcnt(1)
	v_mfma_f32_32x32x16_bf16 v[82:97], v[188:191], v[102:105], v[82:97]
	s_waitcnt lgkmcnt(0)
	v_mfma_f32_32x32x16_bf16 v[66:81], v[192:195], v[102:105], v[66:81]
	ds_read_b128 v[188:191], v177 offset:40960
	ds_read_b128 v[192:195], v177 offset:45056
	s_waitcnt lgkmcnt(1)
	v_mfma_f32_32x32x16_bf16 v[82:97], v[188:191], v[98:101], v[82:97]
	s_waitcnt lgkmcnt(0)
; DI void partialSM(f32x16& p0, f32x16& p1, float& m_reg, float& mn, float& alpha, const float SCALE) {
;   const float C = SCALE * 1.4426950408889634f;
;   float pmax = p0[0];
; #pragma unroll
;   for (int r = 1; r < 16; ++r) pmax = fmaxf(pmax, p0[r]);
; #pragma unroll
;   for (int r = 0; r < 16; ++r) pmax = fmaxf(pmax, p1[r]);
;   { auto rr = __builtin_amdgcn_permlane32_swap(__float_as_uint(pmax), __float_as_uint(pmax), false, false);
;     pmax = fmaxf(__uint_as_float(rr[0]), __uint_as_float(rr[1])); }
;   if (__builtin_expect(__all(pmax - m_reg <= THR / SCALE), 1)) { mn = m_reg; alpha = 1.f; }
;   else { mn = fmaxf(m_reg, pmax); alpha = __builtin_amdgcn_exp2f((m_reg - mn) * C); m_reg = mn; }
;   const float mnC = -mn * C;
; #pragma unroll
;   for (int r = 0; r < 16; ++r) p0[r] = fmaf(p0[r], C, mnC);
; #pragma unroll
;   for (int r = 0; r < 16; ++r) p1[r] = fmaf(p1[r], C, mnC);
; #pragma unroll
;   for (int r = 0; r < 16; ++r) p0[r] = __builtin_amdgcn_exp2f(p0[r]);
; }
; DI void finishSM(f32x16& p0, f32x16& p1, float alpha, float& l_reg, bf16x8& pa0, bf16x8& pa1, bf16x8& pa2, bf16x8& pa3) {
; #pragma unroll
;   for (int r = 0; r < 16; ++r) p1[r] = __builtin_amdgcn_exp2f(p1[r]);
;   float ps = 0;
; #pragma unroll
;   for (int r = 0; r < 16; ++r) ps += p0[r];
; #pragma unroll
;   for (int r = 0; r < 16; ++r) ps += p1[r];
;   { auto rr = __builtin_amdgcn_permlane32_swap(__float_as_uint(ps), __float_as_uint(ps), false, false);
;     ps = __uint_as_float(rr[0]) + __uint_as_float(rr[1]); }
;   l_reg = l_reg * alpha + ps;
;     ...
;   PK4(p0, 0, pa0); PK4(p0, 8, pa1); PK4(p1, 0, pa2); PK4(p1, 8, pa3);
;     ...
; }
	v_mfma_f32_32x32x16_bf16 v[66:81], v[192:195], v[98:101], v[66:81]
	s_nop 7
	s_nop 7
	v_max3_f32 v203, v82, v83, v84
	v_max3_f32 v204, v85, v86, v87
	v_max3_f32 v203, v203, v88, v89
	v_max3_f32 v204, v204, v90, v91
	v_max3_f32 v203, v203, v92, v93
	v_max3_f32 v204, v204, v94, v95
	v_max3_f32 v203, v203, v96, v97
	v_max3_f32 v204, v204, v66, v67
	v_max3_f32 v203, v203, v68, v69
	v_max3_f32 v204, v204, v70, v71
	v_max3_f32 v203, v203, v72, v73
	v_max3_f32 v204, v204, v74, v75
	v_max3_f32 v203, v203, v76, v77
	v_max3_f32 v204, v204, v78, v79
	v_max3_f32 v203, v203, v80, v81
	v_max_f32_e32 v203, v203, v204
	v_mov_b32_e32 v204, v203
	s_nop 1
	v_permlane32_swap_b32_e32 v203, v204
	v_max_f32_e32 v203, v203, v204
	v_max_f32_e32 v203, v206, v203
	v_sub_f32_e32 v204, v206, v203
	v_exp_f32_e32 v152, v204
	v_mov_b32_e32 v206, v203
	v_mul_f32_e32 v205, 0xbf800000, v203
	v_mov_b32_e32 v214, v205
	v_mov_b32_e32 v215, v205
	v_mov_b32_e32 v216, v205
	v_mov_b32_e32 v217, v205
	v_mov_b32_e32 v218, v205
	v_mov_b32_e32 v219, v205
	v_mov_b32_e32 v220, v205
	v_mov_b32_e32 v221, v205
	v_mov_b32_e32 v222, v205
	v_mov_b32_e32 v223, v205
	v_mov_b32_e32 v224, v205
	v_mov_b32_e32 v225, v205
	v_mov_b32_e32 v226, v205
	v_mov_b32_e32 v227, v205
	v_mov_b32_e32 v228, v205
	v_mov_b32_e32 v229, v205
	v_add_f32_e32 v82, v205, v82
	v_add_f32_e32 v83, v205, v83
	v_add_f32_e32 v84, v205, v84
	v_add_f32_e32 v85, v205, v85
	v_add_f32_e32 v86, v205, v86
	v_add_f32_e32 v87, v205, v87
	v_add_f32_e32 v88, v205, v88
	v_add_f32_e32 v89, v205, v89
	v_add_f32_e32 v90, v205, v90
	v_add_f32_e32 v91, v205, v91
	v_add_f32_e32 v92, v205, v92
	v_add_f32_e32 v93, v205, v93
	v_add_f32_e32 v94, v205, v94
	v_add_f32_e32 v95, v205, v95
	v_add_f32_e32 v96, v205, v96
	v_add_f32_e32 v97, v205, v97
	v_add_f32_e32 v66, v205, v66
	v_add_f32_e32 v67, v205, v67
	v_add_f32_e32 v68, v205, v68
	v_add_f32_e32 v69, v205, v69
	v_add_f32_e32 v70, v205, v70
	v_add_f32_e32 v71, v205, v71
	v_add_f32_e32 v72, v205, v72
	v_add_f32_e32 v73, v205, v73
	v_add_f32_e32 v74, v205, v74
	v_add_f32_e32 v75, v205, v75
	v_add_f32_e32 v76, v205, v76
	v_add_f32_e32 v77, v205, v77
	v_add_f32_e32 v78, v205, v78
	v_add_f32_e32 v79, v205, v79
	v_add_f32_e32 v80, v205, v80
	v_add_f32_e32 v81, v205, v81
	v_exp_f32_e32 v82, v82
	v_exp_f32_e32 v83, v83
	v_exp_f32_e32 v84, v84
	v_exp_f32_e32 v85, v85
	v_exp_f32_e32 v86, v86
	v_exp_f32_e32 v87, v87
	v_exp_f32_e32 v88, v88
	v_exp_f32_e32 v89, v89
	v_exp_f32_e32 v90, v90
	v_exp_f32_e32 v91, v91
	v_exp_f32_e32 v92, v92
	v_exp_f32_e32 v93, v93
	v_exp_f32_e32 v94, v94
	v_exp_f32_e32 v95, v95
	v_exp_f32_e32 v96, v96
	v_exp_f32_e32 v97, v97
	v_exp_f32_e32 v66, v66
	v_exp_f32_e32 v67, v67
	v_exp_f32_e32 v68, v68
	v_exp_f32_e32 v69, v69
	v_exp_f32_e32 v70, v70
	v_exp_f32_e32 v71, v71
	v_exp_f32_e32 v72, v72
	v_exp_f32_e32 v73, v73
	v_exp_f32_e32 v74, v74
	v_exp_f32_e32 v75, v75
	v_exp_f32_e32 v76, v76
	v_exp_f32_e32 v77, v77
	v_exp_f32_e32 v78, v78
	v_exp_f32_e32 v79, v79
	v_exp_f32_e32 v80, v80
	v_exp_f32_e32 v81, v81
	s_nop 0
	v_add_f32_e32 v180, v82, v83
	v_add_f32_e32 v180, v84, v180
	v_add_f32_e32 v180, v85, v180
	v_add_f32_e32 v180, v86, v180
	v_add_f32_e32 v180, v87, v180
	v_add_f32_e32 v180, v88, v180
	v_add_f32_e32 v180, v89, v180
	v_add_f32_e32 v180, v90, v180
	v_add_f32_e32 v180, v91, v180
	v_add_f32_e32 v180, v92, v180
	v_add_f32_e32 v180, v93, v180
	v_add_f32_e32 v180, v94, v180
	v_add_f32_e32 v180, v95, v180
	v_add_f32_e32 v180, v96, v180
	v_add_f32_e32 v180, v97, v180
	v_add_f32_e32 v180, v66, v180
	v_add_f32_e32 v180, v67, v180
	v_add_f32_e32 v180, v68, v180
	v_add_f32_e32 v180, v69, v180
	v_add_f32_e32 v180, v70, v180
	v_add_f32_e32 v180, v71, v180
	v_add_f32_e32 v180, v72, v180
	v_add_f32_e32 v180, v73, v180
	v_add_f32_e32 v180, v74, v180
	v_add_f32_e32 v180, v75, v180
	v_add_f32_e32 v180, v76, v180
	v_add_f32_e32 v180, v77, v180
	v_add_f32_e32 v180, v78, v180
	v_add_f32_e32 v180, v79, v180
	v_add_f32_e32 v180, v80, v180
	v_add_f32_e32 v180, v81, v180
	v_fma_f32 v207, v152, v170, v180
	v_cvt_pk_bf16_f32 v208, v82, v83
	v_cvt_pk_bf16_f32 v209, v84, v85
	v_cvt_pk_bf16_f32 v210, v86, v87
	v_cvt_pk_bf16_f32 v211, v88, v89
	v_cvt_pk_bf16_f32 v244, v90, v91
	v_cvt_pk_bf16_f32 v245, v92, v93
	v_cvt_pk_bf16_f32 v246, v94, v95
	v_cvt_pk_bf16_f32 v247, v96, v97
	v_cvt_pk_bf16_f32 v248, v66, v67
	v_cvt_pk_bf16_f32 v249, v68, v69
	v_cvt_pk_bf16_f32 v250, v70, v71
	v_cvt_pk_bf16_f32 v251, v72, v73
	v_cvt_pk_bf16_f32 v182, v74, v75
	v_cvt_pk_bf16_f32 v183, v76, v77
	v_cvt_pk_bf16_f32 v184, v78, v79
	v_cvt_pk_bf16_f32 v185, v80, v81
	s_and_saveexec_b64 s[10:11], s[0:1]
	ds_write_b32 v168, v152 offset:49280
	s_or_b64 exec, exec, s[10:11]
	s_waitcnt lgkmcnt(0)
	v_add_u32_e32 v179, v157, v0
	ds_read_b128 v[186:189], v179 offset:49376
	ds_read_b128 v[190:193], v179 offset:49344
	ds_read_b128 v[194:197], v179 offset:49312
	ds_read_b128 v[198:201], v179 offset:49280
	s_waitcnt lgkmcnt(3)
	v_pk_mul_f32 v[14:15], v[14:15], v[186:187]
	s_waitcnt lgkmcnt(2)
	v_pk_mul_f32 v[10:11], v[10:11], v[190:191]
	s_waitcnt lgkmcnt(1)
	v_pk_mul_f32 v[6:7], v[6:7], v[194:195]
	v_pk_mul_f32 v[16:17], v[16:17], v[188:189]
	v_pk_mul_f32 v[12:13], v[12:13], v[192:193]
	v_pk_mul_f32 v[8:9], v[8:9], v[196:197]
	s_waitcnt lgkmcnt(0)
	v_pk_mul_f32 v[4:5], v[4:5], v[200:201]
	v_pk_mul_f32 v[2:3], v[2:3], v[198:199]
	v_pk_mul_f32 v[62:63], v[62:63], v[186:187]
	v_pk_mul_f32 v[58:59], v[58:59], v[190:191]
	v_pk_mul_f32 v[54:55], v[54:55], v[194:195]
	v_pk_mul_f32 v[64:65], v[64:65], v[188:189]
	v_pk_mul_f32 v[60:61], v[60:61], v[192:193]
	v_pk_mul_f32 v[56:57], v[56:57], v[196:197]
	v_pk_mul_f32 v[52:53], v[52:53], v[200:201]
	v_pk_mul_f32 v[50:51], v[50:51], v[198:199]
	v_pk_mul_f32 v[46:47], v[46:47], v[186:187]
	v_pk_mul_f32 v[42:43], v[42:43], v[190:191]
	v_pk_mul_f32 v[38:39], v[38:39], v[194:195]
	v_pk_mul_f32 v[48:49], v[48:49], v[188:189]
	v_pk_mul_f32 v[44:45], v[44:45], v[192:193]
	v_pk_mul_f32 v[40:41], v[40:41], v[196:197]
	v_pk_mul_f32 v[36:37], v[36:37], v[200:201]
	v_pk_mul_f32 v[34:35], v[34:35], v[198:199]
	v_pk_mul_f32 v[30:31], v[30:31], v[186:187]
	v_pk_mul_f32 v[26:27], v[26:27], v[190:191]
	v_pk_mul_f32 v[22:23], v[22:23], v[194:195]
	v_pk_mul_f32 v[32:33], v[32:33], v[188:189]
	v_pk_mul_f32 v[28:29], v[28:29], v[192:193]
	v_pk_mul_f32 v[24:25], v[24:25], v[196:197]
	v_pk_mul_f32 v[20:21], v[20:21], v[200:201]
	v_pk_mul_f32 v[18:19], v[18:19], v[198:199]

; #define SBAR() __builtin_amdgcn_sched_barrier(0)
; DI void finishSM(f32x16& p0, f32x16& p1, float alpha, float& l_reg, bf16x8& pa0, bf16x8& pa1, bf16x8& pa2, bf16x8& pa3) {
; #pragma unroll
;   for (int r = 0; r < 16; ++r) p1[r] = __builtin_amdgcn_exp2f(p1[r]);
;   float ps = 0;
; #pragma unroll
;   for (int r = 0; r < 16; ++r) ps += p0[r];
; #pragma unroll
;   for (int r = 0; r < 16; ++r) ps += p1[r];
;   { auto rr = __builtin_amdgcn_permlane32_swap(__float_as_uint(ps), __float_as_uint(ps), false, false);
;     ps = __uint_as_float(rr[0]) + __uint_as_float(rr[1]); }
;   l_reg = l_reg * alpha + ps;
;     ...
;   PK4(p0, 0, pa0); PK4(p0, 8, pa1); PK4(p1, 0, pa2); PK4(p1, 8, pa3);
; DI int v_st(int k, int c) { const int kk = (k & ~0xC) | ((k & 4) << 1) | ((k & 8) >> 1); return ((kk >> 3) * 4 + (c >> 5)) * 512 + ((kk & 7) * 32 + (c & 31)) * 2; }
; DI int v_rd_base(int lane) { return ((lane & 3) << 3) | (((lane >> 2) & 3) << 6) | (((lane >> 4) & 1) << 5) | (((lane >> 5) & 1) << 8); }
; template <int OFF> DI s16x4 tr_read(int vb) { s16x4 r; asm volatile("ds_read_b64_tr_b16 %0, %1 offset:%2" : "=&v"(r) : "v"(vb), "i"(OFF) : "memory"); return r; }
; template <int D0> DI void pv_one(f32x16& od, int vb, bf16x8 pa0, bf16x8 pa1, bf16x8 pa2, bf16x8 pa3) {
;   const s16x4 l0 = tr_read<v_rd_off(D0, 0, 0)>(vb), h0 = tr_read<v_rd_off(D0, 0, 1)>(vb), l1 = tr_read<v_rd_off(D0, 1, 0)>(vb), h1 = tr_read<v_rd_off(D0, 1, 1)>(vb);
;   const s16x4 l2 = tr_read<v_rd_off(D0, 2, 0)>(vb), h2 = tr_read<v_rd_off(D0, 2, 1)>(vb), l3 = tr_read<v_rd_off(D0, 3, 0)>(vb), h3 = tr_read<v_rd_off(D0, 3, 1)>(vb);
;   asm volatile("s_waitcnt lgkmcnt(0)" ::: "memory"); SBAR();
;     ...
;   od = __builtin_amdgcn_mfma_f32_32x32x16_bf16(pa0, PK(l0, h0), od, 0, 0, 0);
;   od = __builtin_amdgcn_mfma_f32_32x32x16_bf16(pa1, PK(l1, h1), od, 0, 0, 0);
;   od = __builtin_amdgcn_mfma_f32_32x32x16_bf16(pa2, PK(l2, h2), od, 0, 0, 0);
;   od = __builtin_amdgcn_mfma_f32_32x32x16_bf16(pa3, PK(l3, h3), od, 0, 0, 0);
;     ...
; }
; DI void pv_d0(f32x16* o, int vb, bf16x8 pa0, bf16x8 pa1, bf16x8 pa2, bf16x8 pa3) {
;   pv_one<0>(o[0], vb, pa0, pa1, pa2, pa3); pv_one<1>(o[1], vb, pa0, pa1, pa2, pa3); pv_one<2>(o[2], vb, pa0, pa1, pa2, pa3); pv_one<3>(o[3], vb, pa0, pa1, pa2, pa3);
; }
.LBB0_788:
	ds_read_b64_tr_b16 v[186:187], v231 offset:0x0
	ds_read_b64_tr_b16 v[188:189], v231 offset:0x100
	ds_read_b64_tr_b16 v[190:191], v231 offset:0x1000
	ds_read_b64_tr_b16 v[192:193], v231 offset:0x1100
	ds_read_b64_tr_b16 v[194:195], v231 offset:0x2000
	ds_read_b64_tr_b16 v[196:197], v231 offset:0x2100
	ds_read_b64_tr_b16 v[198:199], v231 offset:0x3000
	ds_read_b64_tr_b16 v[200:201], v231 offset:0x3100
	s_waitcnt lgkmcnt(0)
	v_mfma_f32_32x32x16_bf16 v[2:17], v[208:211], v[186:189], v[2:17]
	ds_read_b64_tr_b16 v[186:187], v231 offset:0x200
	ds_read_b64_tr_b16 v[188:189], v231 offset:0x300
	v_exp_f32_e32 v82, v82
	v_exp_f32_e32 v83, v83
	v_exp_f32_e32 v84, v84
	v_exp_f32_e32 v85, v85
	v_exp_f32_e32 v86, v86
	v_mfma_f32_32x32x16_bf16 v[2:17], v[244:247], v[190:193], v[2:17]
	ds_read_b64_tr_b16 v[190:191], v231 offset:0x1200
	ds_read_b64_tr_b16 v[192:193], v231 offset:0x1300
	v_add_f32_e32 v180, v82, v83
	v_exp_f32_e32 v87, v87
	v_add_f32_e32 v180, v84, v180
	v_exp_f32_e32 v88, v88
	v_add_f32_e32 v180, v85, v180
	v_mfma_f32_32x32x16_bf16 v[2:17], v[248:251], v[194:197], v[2:17]
	ds_read_b64_tr_b16 v[194:195], v231 offset:0x2200
	ds_read_b64_tr_b16 v[196:197], v231 offset:0x2300
	v_cvt_pk_bf16_f32 v138, v82, v83
	v_exp_f32_e32 v89, v89
	v_add_f32_e32 v180, v86, v180
	v_exp_f32_e32 v90, v90
	v_add_f32_e32 v180, v87, v180
	v_mfma_f32_32x32x16_bf16 v[2:17], v[182:185], v[198:201], v[2:17]
	ds_read_b64_tr_b16 v[198:199], v231 offset:0x3200
	ds_read_b64_tr_b16 v[200:201], v231 offset:0x3300
	v_cvt_pk_bf16_f32 v139, v84, v85
	v_exp_f32_e32 v91, v91
	v_add_f32_e32 v180, v88, v180
	v_exp_f32_e32 v92, v92
	v_add_f32_e32 v180, v89, v180
	s_waitcnt lgkmcnt(0)
	v_mfma_f32_32x32x16_bf16 v[50:65], v[208:211], v[186:189], v[50:65]
	ds_read_b64_tr_b16 v[186:187], v231 offset:0x400
	ds_read_b64_tr_b16 v[188:189], v231 offset:0x500
	v_cvt_pk_bf16_f32 v140, v86, v87
	v_exp_f32_e32 v93, v93
	v_add_f32_e32 v180, v90, v180
	v_exp_f32_e32 v94, v94
	v_add_f32_e32 v180, v91, v180
	v_mfma_f32_32x32x16_bf16 v[50:65], v[244:247], v[190:193], v[50:65]
	ds_read_b64_tr_b16 v[190:191], v231 offset:0x1400
	ds_read_b64_tr_b16 v[192:193], v231 offset:0x1500
	v_cvt_pk_bf16_f32 v141, v88, v89
	v_exp_f32_e32 v95, v95
	v_add_f32_e32 v180, v92, v180
	v_exp_f32_e32 v96, v96
	v_add_f32_e32 v180, v93, v180
	v_mfma_f32_32x32x16_bf16 v[50:65], v[248:251], v[194:197], v[50:65]
	ds_read_b64_tr_b16 v[194:195], v231 offset:0x2400
	ds_read_b64_tr_b16 v[196:197], v231 offset:0x2500
	v_cvt_pk_bf16_f32 v144, v90, v91
	v_exp_f32_e32 v97, v97
	v_add_f32_e32 v180, v94, v180
	v_exp_f32_e32 v66, v66
	v_add_f32_e32 v180, v95, v180
	v_mfma_f32_32x32x16_bf16 v[50:65], v[182:185], v[198:201], v[50:65]
	ds_read_b64_tr_b16 v[198:199], v231 offset:0x3400
	ds_read_b64_tr_b16 v[200:201], v231 offset:0x3500
	v_cvt_pk_bf16_f32 v145, v92, v93
	v_exp_f32_e32 v67, v67
	v_add_f32_e32 v180, v96, v180
	v_exp_f32_e32 v68, v68
	v_add_f32_e32 v180, v97, v180
	s_waitcnt lgkmcnt(0)
	v_mfma_f32_32x32x16_bf16 v[34:49], v[208:211], v[186:189], v[34:49]
	ds_read_b64_tr_b16 v[186:187], v231 offset:0x600
	ds_read_b64_tr_b16 v[188:189], v231 offset:0x700
	v_cvt_pk_bf16_f32 v146, v94, v95
	v_exp_f32_e32 v69, v69
	v_add_f32_e32 v180, v66, v180
	v_exp_f32_e32 v70, v70
	v_add_f32_e32 v180, v67, v180
	v_cvt_pk_bf16_f32 v147, v96, v97
	v_mfma_f32_32x32x16_bf16 v[34:49], v[244:247], v[190:193], v[34:49]
	ds_read_b64_tr_b16 v[190:191], v231 offset:0x1600
	ds_read_b64_tr_b16 v[192:193], v231 offset:0x1700
	v_exp_f32_e32 v71, v71
	v_add_f32_e32 v180, v68, v180
	v_exp_f32_e32 v72, v72
	v_add_f32_e32 v180, v69, v180
	v_cvt_pk_bf16_f32 v148, v66, v67
	v_mfma_f32_32x32x16_bf16 v[34:49], v[248:251], v[194:197], v[34:49]
	ds_read_b64_tr_b16 v[194:195], v231 offset:0x2600
	ds_read_b64_tr_b16 v[196:197], v231 offset:0x2700
	v_exp_f32_e32 v73, v73
	v_add_f32_e32 v180, v70, v180
	v_exp_f32_e32 v74, v74
	v_add_f32_e32 v180, v71, v180
	v_cvt_pk_bf16_f32 v149, v68, v69
	v_mfma_f32_32x32x16_bf16 v[34:49], v[182:185], v[198:201], v[34:49]
	ds_read_b64_tr_b16 v[198:199], v231 offset:0x3600
	ds_read_b64_tr_b16 v[200:201], v231 offset:0x3700
	v_exp_f32_e32 v75, v75
	v_add_f32_e32 v180, v72, v180
	v_exp_f32_e32 v76, v76
	v_add_f32_e32 v180, v73, v180
	v_cvt_pk_bf16_f32 v150, v70, v71
	s_waitcnt lgkmcnt(0)
	v_mfma_f32_32x32x16_bf16 v[18:33], v[208:211], v[186:189], v[18:33]
	v_exp_f32_e32 v77, v77
	v_add_f32_e32 v180, v74, v180
	v_exp_f32_e32 v78, v78
	v_add_f32_e32 v180, v75, v180
	v_cvt_pk_bf16_f32 v151, v72, v73
	v_mfma_f32_32x32x16_bf16 v[18:33], v[244:247], v[190:193], v[18:33]
	v_exp_f32_e32 v79, v79
	v_add_f32_e32 v180, v76, v180
	v_exp_f32_e32 v80, v80
	v_add_f32_e32 v180, v77, v180
	v_cvt_pk_bf16_f32 v162, v74, v75
	v_mfma_f32_32x32x16_bf16 v[18:33], v[248:251], v[194:197], v[18:33]
	v_exp_f32_e32 v81, v81
	v_add_f32_e32 v180, v78, v180
	v_add_f32_e32 v180, v79, v180
	v_cvt_pk_bf16_f32 v163, v76, v77
	v_add_f32_e32 v180, v80, v180
	v_mfma_f32_32x32x16_bf16 v[18:33], v[182:185], v[198:201], v[18:33]
	v_add_f32_e32 v180, v81, v180
	v_cvt_pk_bf16_f32 v164, v78, v79
	v_cvt_pk_bf16_f32 v165, v80, v81
	v_cmp_nge_f32_e32 vcc, 0x453a4f54, v180
	v_add_f32_e32 v170, v207, v180
	v_mov_b32_e32 v143, 1.0
	s_barrier
	s_waitcnt vmcnt(3)
	s_waitcnt vmcnt(2)
	ds_write_b128 v172, v[126:129] offset:16384
	s_waitcnt vmcnt(1)
	ds_write_b128 v173, v[130:133] offset:16384
	s_waitcnt vmcnt(0)
	ds_write_b128 v174, v[134:137] offset:40960
	s_cbranch_vccz .LBB0_792
; DI void partialSM(f32x16& p0, f32x16& p1, float& m_reg, float& mn, float& alpha, const float SCALE) {
;   const float C = SCALE * 1.4426950408889634f;
;   float pmax = p0[0];
; #pragma unroll
;   for (int r = 1; r < 16; ++r) pmax = fmaxf(pmax, p0[r]);
; #pragma unroll
;   for (int r = 0; r < 16; ++r) pmax = fmaxf(pmax, p1[r]);
;   { auto rr = __builtin_amdgcn_permlane32_swap(__float_as_uint(pmax), __float_as_uint(pmax), false, false);
;     pmax = fmaxf(__uint_as_float(rr[0]), __uint_as_float(rr[1])); }
;   if (__builtin_expect(__all(pmax - m_reg <= THR / SCALE), 1)) { mn = m_reg; alpha = 1.f; }
;   else { mn = fmaxf(m_reg, pmax); alpha = __builtin_amdgcn_exp2f((m_reg - mn) * C); m_reg = mn; }
;   const float mnC = -mn * C;
; #pragma unroll
;   for (int r = 0; r < 16; ++r) p0[r] = fmaf(p0[r], C, mnC);
; #pragma unroll
;   for (int r = 0; r < 16; ++r) p1[r] = fmaf(p1[r], C, mnC);
; #pragma unroll
;   for (int r = 0; r < 16; ++r) p0[r] = __builtin_amdgcn_exp2f(p0[r]);
; }
; DI void finishSM(f32x16& p0, f32x16& p1, float alpha, float& l_reg, bf16x8& pa0, bf16x8& pa1, bf16x8& pa2, bf16x8& pa3) {
; #pragma unroll
;   for (int r = 0; r < 16; ++r) p1[r] = __builtin_amdgcn_exp2f(p1[r]);
;   float ps = 0;
; #pragma unroll
;   for (int r = 0; r < 16; ++r) ps += p0[r];
; #pragma unroll
;   for (int r = 0; r < 16; ++r) ps += p1[r];
;   { auto rr = __builtin_amdgcn_permlane32_swap(__float_as_uint(ps), __float_as_uint(ps), false, false);
;     ps = __uint_as_float(rr[0]) + __uint_as_float(rr[1]); }
;   l_reg = l_reg * alpha + ps;
;     ...
;   PK4(p0, 0, pa0); PK4(p0, 8, pa1); PK4(p1, 0, pa2); PK4(p1, 8, pa3);
;     ...
; }
	ds_read_b128 v[66:69], v175 offset:32768
	ds_read_b128 v[70:73], v175 offset:36864
	ds_read_b128 v[188:191], v176 offset:32768
	ds_read_b128 v[192:195], v176 offset:36864
	s_waitcnt lgkmcnt(3)
	v_mfma_f32_32x32x16_bf16 v[82:97], v[66:69], v[110:113], 0
	s_waitcnt lgkmcnt(2)
	v_mfma_f32_32x32x16_bf16 v[66:81], v[70:73], v[110:113], 0
	s_waitcnt lgkmcnt(1)
	v_mfma_f32_32x32x16_bf16 v[82:97], v[188:191], v[106:109], v[82:97]
	s_waitcnt lgkmcnt(0)
	v_mfma_f32_32x32x16_bf16 v[66:81], v[192:195], v[106:109], v[66:81]
	ds_read_b128 v[188:191], v178 offset:32768
	ds_read_b128 v[192:195], v178 offset:36864
	s_waitcnt lgkmcnt(1)
	v_mfma_f32_32x32x16_bf16 v[82:97], v[188:191], v[102:105], v[82:97]
	s_waitcnt lgkmcnt(0)
	v_mfma_f32_32x32x16_bf16 v[66:81], v[192:195], v[102:105], v[66:81]
	ds_read_b128 v[188:191], v177 offset:32768
	ds_read_b128 v[192:195], v177 offset:36864
	s_waitcnt lgkmcnt(1)
	v_mfma_f32_32x32x16_bf16 v[82:97], v[188:191], v[98:101], v[82:97]
	s_waitcnt lgkmcnt(0)
	v_mfma_f32_32x32x16_bf16 v[66:81], v[192:195], v[98:101], v[66:81]
	s_nop 7
	s_nop 7
	v_max3_f32 v203, v82, v83, v84
	v_max3_f32 v204, v85, v86, v87
	v_max3_f32 v203, v203, v88, v89
	v_max3_f32 v204, v204, v90, v91
	v_max3_f32 v203, v203, v92, v93
	v_max3_f32 v204, v204, v94, v95
	v_max3_f32 v203, v203, v96, v97
	v_max3_f32 v204, v204, v66, v67
	v_max3_f32 v203, v203, v68, v69
	v_max3_f32 v204, v204, v70, v71
	v_max3_f32 v203, v203, v72, v73
	v_max3_f32 v204, v204, v74, v75
	v_max3_f32 v203, v203, v76, v77
	v_max3_f32 v204, v204, v78, v79
	v_max3_f32 v203, v203, v80, v81
	v_max_f32_e32 v203, v203, v204
	v_mov_b32_e32 v204, v203
	s_nop 1
	v_permlane32_swap_b32_e32 v203, v204
	v_max_f32_e32 v203, v203, v204
	v_max_f32_e32 v203, v206, v203
	v_sub_f32_e32 v204, v206, v203
	v_exp_f32_e32 v143, v204
	v_mov_b32_e32 v206, v203
	v_mul_f32_e32 v205, 0xbf800000, v203
	v_mov_b32_e32 v214, v205
	v_mov_b32_e32 v215, v205
	v_mov_b32_e32 v216, v205
	v_mov_b32_e32 v217, v205
	v_mov_b32_e32 v218, v205
	v_mov_b32_e32 v219, v205
	v_mov_b32_e32 v220, v205
	v_mov_b32_e32 v221, v205
	v_mov_b32_e32 v222, v205
	v_mov_b32_e32 v223, v205
	v_mov_b32_e32 v224, v205
	v_mov_b32_e32 v225, v205
	v_mov_b32_e32 v226, v205
	v_mov_b32_e32 v227, v205
	v_mov_b32_e32 v228, v205
	v_mov_b32_e32 v229, v205
	v_add_f32_e32 v82, v205, v82
	v_add_f32_e32 v83, v205, v83
	v_add_f32_e32 v84, v205, v84
	v_add_f32_e32 v85, v205, v85
	v_add_f32_e32 v86, v205, v86
	v_add_f32_e32 v87, v205, v87
	v_add_f32_e32 v88, v205, v88
	v_add_f32_e32 v89, v205, v89
	v_add_f32_e32 v90, v205, v90
	v_add_f32_e32 v91, v205, v91
	v_add_f32_e32 v92, v205, v92
	v_add_f32_e32 v93, v205, v93
	v_add_f32_e32 v94, v205, v94
	v_add_f32_e32 v95, v205, v95
	v_add_f32_e32 v96, v205, v96
	v_add_f32_e32 v97, v205, v97
	v_add_f32_e32 v66, v205, v66
	v_add_f32_e32 v67, v205, v67
	v_add_f32_e32 v68, v205, v68
	v_add_f32_e32 v69, v205, v69
	v_add_f32_e32 v70, v205, v70
	v_add_f32_e32 v71, v205, v71
	v_add_f32_e32 v72, v205, v72
	v_add_f32_e32 v73, v205, v73
	v_add_f32_e32 v74, v205, v74
	v_add_f32_e32 v75, v205, v75
	v_add_f32_e32 v76, v205, v76
	v_add_f32_e32 v77, v205, v77
	v_add_f32_e32 v78, v205, v78
	v_add_f32_e32 v79, v205, v79
	v_add_f32_e32 v80, v205, v80
	v_add_f32_e32 v81, v205, v81
	v_exp_f32_e32 v82, v82
	v_exp_f32_e32 v83, v83
	v_exp_f32_e32 v84, v84
	v_exp_f32_e32 v85, v85
	v_exp_f32_e32 v86, v86
	v_exp_f32_e32 v87, v87
	v_exp_f32_e32 v88, v88
	v_exp_f32_e32 v89, v89
	v_exp_f32_e32 v90, v90
	v_exp_f32_e32 v91, v91
	v_exp_f32_e32 v92, v92
	v_exp_f32_e32 v93, v93
	v_exp_f32_e32 v94, v94
	v_exp_f32_e32 v95, v95
	v_exp_f32_e32 v96, v96
	v_exp_f32_e32 v97, v97
	v_exp_f32_e32 v66, v66
	v_exp_f32_e32 v67, v67
	v_exp_f32_e32 v68, v68
	v_exp_f32_e32 v69, v69
	v_exp_f32_e32 v70, v70
	v_exp_f32_e32 v71, v71
	v_exp_f32_e32 v72, v72
	v_exp_f32_e32 v73, v73
	v_exp_f32_e32 v74, v74
	v_exp_f32_e32 v75, v75
	v_exp_f32_e32 v76, v76
	v_exp_f32_e32 v77, v77
	v_exp_f32_e32 v78, v78
	v_exp_f32_e32 v79, v79
	v_exp_f32_e32 v80, v80
	v_exp_f32_e32 v81, v81
	s_nop 0
	v_add_f32_e32 v180, v82, v83
	v_add_f32_e32 v180, v84, v180
	v_add_f32_e32 v180, v85, v180
	v_add_f32_e32 v180, v86, v180
	v_add_f32_e32 v180, v87, v180
	v_add_f32_e32 v180, v88, v180
	v_add_f32_e32 v180, v89, v180
	v_add_f32_e32 v180, v90, v180
	v_add_f32_e32 v180, v91, v180
	v_add_f32_e32 v180, v92, v180
	v_add_f32_e32 v180, v93, v180
	v_add_f32_e32 v180, v94, v180
	v_add_f32_e32 v180, v95, v180
	v_add_f32_e32 v180, v96, v180
	v_add_f32_e32 v180, v97, v180
	v_add_f32_e32 v180, v66, v180
	v_add_f32_e32 v180, v67, v180
	v_add_f32_e32 v180, v68, v180
	v_add_f32_e32 v180, v69, v180
	v_add_f32_e32 v180, v70, v180
	v_add_f32_e32 v180, v71, v180
	v_add_f32_e32 v180, v72, v180
	v_add_f32_e32 v180, v73, v180
	v_add_f32_e32 v180, v74, v180
	v_add_f32_e32 v180, v75, v180
	v_add_f32_e32 v180, v76, v180
	v_add_f32_e32 v180, v77, v180
	v_add_f32_e32 v180, v78, v180
	v_add_f32_e32 v180, v79, v180
	v_add_f32_e32 v180, v80, v180
	v_add_f32_e32 v180, v81, v180
	v_fma_f32 v170, v143, v207, v180
	v_cvt_pk_bf16_f32 v138, v82, v83
	v_cvt_pk_bf16_f32 v139, v84, v85
	v_cvt_pk_bf16_f32 v140, v86, v87
	v_cvt_pk_bf16_f32 v141, v88, v89
	v_cvt_pk_bf16_f32 v144, v90, v91
	v_cvt_pk_bf16_f32 v145, v92, v93
	v_cvt_pk_bf16_f32 v146, v94, v95
	v_cvt_pk_bf16_f32 v147, v96, v97
	v_cvt_pk_bf16_f32 v148, v66, v67
	v_cvt_pk_bf16_f32 v149, v68, v69
	v_cvt_pk_bf16_f32 v150, v70, v71
	v_cvt_pk_bf16_f32 v151, v72, v73
	v_cvt_pk_bf16_f32 v162, v74, v75
	v_cvt_pk_bf16_f32 v163, v76, v77
	v_cvt_pk_bf16_f32 v164, v78, v79
	v_cvt_pk_bf16_f32 v165, v80, v81
	s_and_saveexec_b64 s[12:13], s[0:1]
	ds_write_b32 v168, v143 offset:49280
	s_or_b64 exec, exec, s[12:13]
	s_waitcnt lgkmcnt(0)
	v_add_u32_e32 v179, v157, v0
	ds_read_b128 v[186:189], v179 offset:49376
	ds_read_b128 v[190:193], v179 offset:49344
	ds_read_b128 v[194:197], v179 offset:49312
	ds_read_b128 v[198:201], v179 offset:49280
	s_waitcnt lgkmcnt(3)
	v_pk_mul_f32 v[14:15], v[14:15], v[186:187]
	s_waitcnt lgkmcnt(2)
	v_pk_mul_f32 v[10:11], v[10:11], v[190:191]
	s_waitcnt lgkmcnt(1)
	v_pk_mul_f32 v[6:7], v[6:7], v[194:195]
	v_pk_mul_f32 v[16:17], v[16:17], v[188:189]
	v_pk_mul_f32 v[12:13], v[12:13], v[192:193]
	v_pk_mul_f32 v[8:9], v[8:9], v[196:197]
	s_waitcnt lgkmcnt(0)
	v_pk_mul_f32 v[4:5], v[4:5], v[200:201]
	v_pk_mul_f32 v[2:3], v[2:3], v[198:199]
	v_pk_mul_f32 v[62:63], v[62:63], v[186:187]
	v_pk_mul_f32 v[58:59], v[58:59], v[190:191]
	v_pk_mul_f32 v[54:55], v[54:55], v[194:195]
	v_pk_mul_f32 v[64:65], v[64:65], v[188:189]
	v_pk_mul_f32 v[60:61], v[60:61], v[192:193]
	v_pk_mul_f32 v[56:57], v[56:57], v[196:197]
	v_pk_mul_f32 v[52:53], v[52:53], v[200:201]
	v_pk_mul_f32 v[50:51], v[50:51], v[198:199]
	v_pk_mul_f32 v[46:47], v[46:47], v[186:187]
	v_pk_mul_f32 v[42:43], v[42:43], v[190:191]
	v_pk_mul_f32 v[38:39], v[38:39], v[194:195]
	v_pk_mul_f32 v[48:49], v[48:49], v[188:189]
	v_pk_mul_f32 v[44:45], v[44:45], v[192:193]
	v_pk_mul_f32 v[40:41], v[40:41], v[196:197]
	v_pk_mul_f32 v[36:37], v[36:37], v[200:201]
	v_pk_mul_f32 v[34:35], v[34:35], v[198:199]
	v_pk_mul_f32 v[30:31], v[30:31], v[186:187]
	v_pk_mul_f32 v[26:27], v[26:27], v[190:191]
	v_pk_mul_f32 v[22:23], v[22:23], v[194:195]
	v_pk_mul_f32 v[32:33], v[32:33], v[188:189]
	v_pk_mul_f32 v[28:29], v[28:29], v[192:193]
	v_pk_mul_f32 v[24:25], v[24:25], v[196:197]
	v_pk_mul_f32 v[20:21], v[20:21], v[200:201]
	v_pk_mul_f32 v[18:19], v[18:19], v[198:199]

; #define SBAR() __builtin_amdgcn_sched_barrier(0)
; DI void partialSM(f32x16& p0, f32x16& p1, float& m_reg, float& mn, float& alpha, const float SCALE) {
;   const float C = SCALE * 1.4426950408889634f;
;   float pmax = p0[0];
; #pragma unroll
;   for (int r = 1; r < 16; ++r) pmax = fmaxf(pmax, p0[r]);
; #pragma unroll
;   for (int r = 0; r < 16; ++r) pmax = fmaxf(pmax, p1[r]);
;   { auto rr = __builtin_amdgcn_permlane32_swap(__float_as_uint(pmax), __float_as_uint(pmax), false, false);
;     pmax = fmaxf(__uint_as_float(rr[0]), __uint_as_float(rr[1])); }
;   if (__builtin_expect(__all(pmax - m_reg <= THR / SCALE), 1)) { mn = m_reg; alpha = 1.f; }
;   else { mn = fmaxf(m_reg, pmax); alpha = __builtin_amdgcn_exp2f((m_reg - mn) * C); m_reg = mn; }
; DI int v_st(int k, int c) { const int kk = (k & ~0xC) | ((k & 4) << 1) | ((k & 8) >> 1); return ((kk >> 3) * 4 + (c >> 5)) * 512 + ((kk & 7) * 32 + (c & 31)) * 2; }
; DI int v_rd_base(int lane) { return ((lane & 3) << 3) | (((lane >> 2) & 3) << 6) | (((lane >> 4) & 1) << 5) | (((lane >> 5) & 1) << 8); }
; template <int OFF> DI s16x4 tr_read(int vb) { s16x4 r; asm volatile("ds_read_b64_tr_b16 %0, %1 offset:%2" : "=&v"(r) : "v"(vb), "i"(OFF) : "memory"); return r; }
; template <int D0> DI void pv_one(f32x16& od, int vb, bf16x8 pa0, bf16x8 pa1, bf16x8 pa2, bf16x8 pa3) {
;   const s16x4 l0 = tr_read<v_rd_off(D0, 0, 0)>(vb), h0 = tr_read<v_rd_off(D0, 0, 1)>(vb), l1 = tr_read<v_rd_off(D0, 1, 0)>(vb), h1 = tr_read<v_rd_off(D0, 1, 1)>(vb);
;   const s16x4 l2 = tr_read<v_rd_off(D0, 2, 0)>(vb), h2 = tr_read<v_rd_off(D0, 2, 1)>(vb), l3 = tr_read<v_rd_off(D0, 3, 0)>(vb), h3 = tr_read<v_rd_off(D0, 3, 1)>(vb);
;   asm volatile("s_waitcnt lgkmcnt(0)" ::: "memory"); SBAR();
;     ...
;   od = __builtin_amdgcn_mfma_f32_32x32x16_bf16(pa0, PK(l0, h0), od, 0, 0, 0);
;   od = __builtin_amdgcn_mfma_f32_32x32x16_bf16(pa1, PK(l1, h1), od, 0, 0, 0);
;   od = __builtin_amdgcn_mfma_f32_32x32x16_bf16(pa2, PK(l2, h2), od, 0, 0, 0);
;   od = __builtin_amdgcn_mfma_f32_32x32x16_bf16(pa3, PK(l3, h3), od, 0, 0, 0);
;     ...
; }
; DI void pv_d0(f32x16* o, int vb, bf16x8 pa0, bf16x8 pa1, bf16x8 pa2, bf16x8 pa3) {
;   pv_one<0>(o[0], vb, pa0, pa1, pa2, pa3); pv_one<1>(o[1], vb, pa0, pa1, pa2, pa3); pv_one<2>(o[2], vb, pa0, pa1, pa2, pa3); pv_one<3>(o[3], vb, pa0, pa1, pa2, pa3);
; }
.LBB0_794:
	ds_read_b128 v[66:69], v175 offset:40960
	ds_read_b128 v[70:73], v175 offset:45056
	s_waitcnt lgkmcnt(1)
	v_mfma_f32_32x32x16_bf16 v[82:97], v[66:69], v[110:113], 0
	s_waitcnt lgkmcnt(0)
	v_mfma_f32_32x32x16_bf16 v[66:81], v[70:73], v[110:113], 0
	ds_read_b128 v[110:113], v176 offset:40960
	ds_read_b128 v[114:117], v176 offset:45056
	s_waitcnt lgkmcnt(1)
	v_mfma_f32_32x32x16_bf16 v[82:97], v[110:113], v[106:109], v[82:97]
	s_waitcnt lgkmcnt(0)
	v_mfma_f32_32x32x16_bf16 v[66:81], v[114:117], v[106:109], v[66:81]
	ds_read_b128 v[106:109], v178 offset:40960
	ds_read_b128 v[110:113], v178 offset:45056
	s_waitcnt lgkmcnt(1)
	v_mfma_f32_32x32x16_bf16 v[82:97], v[106:109], v[102:105], v[82:97]
	s_waitcnt lgkmcnt(0)
	v_mfma_f32_32x32x16_bf16 v[66:81], v[110:113], v[102:105], v[66:81]
	ds_read_b128 v[102:105], v177 offset:40960
	ds_read_b128 v[106:109], v177 offset:45056
	s_waitcnt lgkmcnt(1)
	v_mfma_f32_32x32x16_bf16 v[82:97], v[102:105], v[98:101], v[82:97]
	s_waitcnt lgkmcnt(0)
	v_mfma_f32_32x32x16_bf16 v[66:81], v[106:109], v[98:101], v[66:81]
	v_mov_b32_e32 v99, v180
	v_mov_b32_e32 v100, v180
	s_nop 1
	v_permlane32_swap_b32_e32 v99, v100
	ds_read_b64_tr_b16 v[118:119], v230 offset:0x0
	ds_read_b64_tr_b16 v[120:121], v230 offset:0x100
	ds_read_b64_tr_b16 v[122:123], v230 offset:0x1000
	ds_read_b64_tr_b16 v[124:125], v230 offset:0x1100
	ds_read_b64_tr_b16 v[126:127], v230 offset:0x2000
	ds_read_b64_tr_b16 v[128:129], v230 offset:0x2100
	ds_read_b64_tr_b16 v[130:131], v230 offset:0x3000
	ds_read_b64_tr_b16 v[132:133], v230 offset:0x3100
	s_waitcnt lgkmcnt(0)
	s_nop 0
	v_mfma_f32_32x32x16_bf16 v[2:17], v[138:141], v[118:121], v[2:17]
	ds_read_b64_tr_b16 v[118:119], v230 offset:0x200
	ds_read_b64_tr_b16 v[120:121], v230 offset:0x300
	v_mfma_f32_32x32x16_bf16 v[2:17], v[144:147], v[122:125], v[2:17]
	ds_read_b64_tr_b16 v[122:123], v230 offset:0x1200
	ds_read_b64_tr_b16 v[124:125], v230 offset:0x1300
	v_mfma_f32_32x32x16_bf16 v[2:17], v[148:151], v[126:129], v[2:17]
	ds_read_b64_tr_b16 v[126:127], v230 offset:0x2200
	ds_read_b64_tr_b16 v[128:129], v230 offset:0x2300
	v_mfma_f32_32x32x16_bf16 v[2:17], v[162:165], v[130:133], v[2:17]
	ds_read_b64_tr_b16 v[130:131], v230 offset:0x3200
	ds_read_b64_tr_b16 v[132:133], v230 offset:0x3300
	s_waitcnt lgkmcnt(0)
	v_mfma_f32_32x32x16_bf16 v[50:65], v[138:141], v[118:121], v[50:65]
	ds_read_b64_tr_b16 v[118:119], v230 offset:0x400
	ds_read_b64_tr_b16 v[120:121], v230 offset:0x500
	v_mfma_f32_32x32x16_bf16 v[50:65], v[144:147], v[122:125], v[50:65]
	ds_read_b64_tr_b16 v[122:123], v230 offset:0x1400
	ds_read_b64_tr_b16 v[124:125], v230 offset:0x1500
	v_mfma_f32_32x32x16_bf16 v[50:65], v[148:151], v[126:129], v[50:65]
	ds_read_b64_tr_b16 v[126:127], v230 offset:0x2400
	ds_read_b64_tr_b16 v[128:129], v230 offset:0x2500
	v_mfma_f32_32x32x16_bf16 v[50:65], v[162:165], v[130:133], v[50:65]
	ds_read_b64_tr_b16 v[130:131], v230 offset:0x3400
	ds_read_b64_tr_b16 v[132:133], v230 offset:0x3500
	s_waitcnt lgkmcnt(0)
	v_mfma_f32_32x32x16_bf16 v[34:49], v[138:141], v[118:121], v[34:49]
	ds_read_b64_tr_b16 v[118:119], v230 offset:0x600
	ds_read_b64_tr_b16 v[120:121], v230 offset:0x700
	v_mfma_f32_32x32x16_bf16 v[34:49], v[144:147], v[122:125], v[34:49]
	ds_read_b64_tr_b16 v[122:123], v230 offset:0x1600
	ds_read_b64_tr_b16 v[124:125], v230 offset:0x1700
	v_mfma_f32_32x32x16_bf16 v[34:49], v[148:151], v[126:129], v[34:49]
	ds_read_b64_tr_b16 v[126:127], v230 offset:0x2600
	ds_read_b64_tr_b16 v[128:129], v230 offset:0x2700
	v_mfma_f32_32x32x16_bf16 v[34:49], v[162:165], v[130:133], v[34:49]
	ds_read_b64_tr_b16 v[130:131], v230 offset:0x3600
	ds_read_b64_tr_b16 v[132:133], v230 offset:0x3700
	s_waitcnt lgkmcnt(0)
	v_mfma_f32_32x32x16_bf16 v[18:33], v[138:141], v[118:121], v[18:33]
	v_max_f32_e32 v98, v83, v83
	v_max_f32_e32 v101, v82, v82
	v_max_f32_e32 v98, v101, v98
	v_max3_f32 v98, v98, v84, v85
	v_max3_f32 v98, v98, v86, v87
	v_max3_f32 v98, v98, v88, v89
	v_max3_f32 v98, v98, v90, v91
	v_max3_f32 v98, v98, v92, v93
	v_max3_f32 v98, v98, v94, v95
	v_mfma_f32_32x32x16_bf16 v[18:33], v[144:147], v[122:125], v[18:33]
	v_max3_f32 v98, v98, v96, v97
	v_max3_f32 v98, v98, v66, v67
	v_max3_f32 v98, v98, v68, v69
	v_max3_f32 v98, v98, v70, v71
	v_max3_f32 v98, v98, v72, v73
	v_max3_f32 v98, v98, v74, v75
	v_max3_f32 v98, v98, v76, v77
	v_max3_f32 v98, v98, v78, v79
	v_mfma_f32_32x32x16_bf16 v[18:33], v[148:151], v[126:129], v[18:33]
	v_max3_f32 v98, v98, v80, v81
	v_mov_b32_e32 v101, v98
	s_nop 1
	v_permlane32_swap_b32_e32 v98, v101
	v_max_f32_e32 v101, v101, v101
	v_max_f32_e32 v98, v98, v98
	v_max_f32_e32 v98, v98, v101
	v_sub_f32_e32 v101, v98, v142
	v_cmp_ge_f32_e32 vcc, 0x4138aa3b, v101
	v_max_f32_e32 v101, v142, v142
	v_max_f32_e32 v98, v101, v98
	v_mfma_f32_32x32x16_bf16 v[18:33], v[162:165], v[130:133], v[18:33]
	v_sub_f32_e32 v101, v142, v98
	v_mul_f32_e32 v101, 0x3f800000, v101
	v_exp_f32_e32 v101, v101
	s_cmp_eq_u64 vcc, exec
	s_cselect_b64 s[2:3], -1, 0
	v_cndmask_b32_e64 v101, v101, 1.0, s[2:3]
	v_cmp_gt_f32_e32 vcc, 1.0, v101
	s_barrier
	s_cbranch_vccz .LBB0_798
	s_and_saveexec_b64 s[10:11], s[0:1]
	ds_write_b32 v168, v101 offset:49280
	s_or_b64 exec, exec, s[10:11]
	s_waitcnt lgkmcnt(0)
	v_add_u32_e32 v114, v157, v0
	ds_read_b128 v[102:105], v114 offset:49376
	ds_read_b128 v[106:109], v114 offset:49344
	ds_read_b128 v[110:113], v114 offset:49312
	ds_read_b128 v[114:117], v114 offset:49280
	s_waitcnt lgkmcnt(3)
	v_pk_mul_f32 v[14:15], v[14:15], v[102:103]
	s_waitcnt lgkmcnt(2)
	v_pk_mul_f32 v[10:11], v[10:11], v[106:107]
	s_waitcnt lgkmcnt(1)
	v_pk_mul_f32 v[6:7], v[6:7], v[110:111]
	v_pk_mul_f32 v[16:17], v[16:17], v[104:105]
	v_pk_mul_f32 v[12:13], v[12:13], v[108:109]
	v_pk_mul_f32 v[8:9], v[8:9], v[112:113]
	s_waitcnt lgkmcnt(0)
	v_pk_mul_f32 v[4:5], v[4:5], v[116:117]
	v_pk_mul_f32 v[2:3], v[2:3], v[114:115]
	v_pk_mul_f32 v[62:63], v[62:63], v[102:103]
	v_pk_mul_f32 v[58:59], v[58:59], v[106:107]
	v_pk_mul_f32 v[54:55], v[54:55], v[110:111]
	v_pk_mul_f32 v[64:65], v[64:65], v[104:105]
	v_pk_mul_f32 v[60:61], v[60:61], v[108:109]
	v_pk_mul_f32 v[56:57], v[56:57], v[112:113]
	v_pk_mul_f32 v[52:53], v[52:53], v[116:117]
	v_pk_mul_f32 v[50:51], v[50:51], v[114:115]
	v_pk_mul_f32 v[46:47], v[46:47], v[102:103]
	v_pk_mul_f32 v[42:43], v[42:43], v[106:107]
	v_pk_mul_f32 v[38:39], v[38:39], v[110:111]
	v_pk_mul_f32 v[48:49], v[48:49], v[104:105]
	v_pk_mul_f32 v[44:45], v[44:45], v[108:109]
	v_pk_mul_f32 v[40:41], v[40:41], v[112:113]
	v_pk_mul_f32 v[36:37], v[36:37], v[116:117]
	v_pk_mul_f32 v[34:35], v[34:35], v[114:115]
	v_pk_mul_f32 v[30:31], v[30:31], v[102:103]
	v_pk_mul_f32 v[26:27], v[26:27], v[106:107]
	v_pk_mul_f32 v[22:23], v[22:23], v[110:111]
	v_pk_mul_f32 v[32:33], v[32:33], v[104:105]
	v_pk_mul_f32 v[28:29], v[28:29], v[108:109]
	v_pk_mul_f32 v[24:25], v[24:25], v[112:113]
	v_pk_mul_f32 v[20:21], v[20:21], v[116:117]
	v_pk_mul_f32 v[18:19], v[18:19], v[114:115]
